# v6 plus counted vmcnt waits at the NA unit header (q and key-scale loads no longer wait for the three prefetched K rows)
# speedup vs baseline: 1.0083x; 1.0004x over previous
; __device__ __forceinline__ float sum_fq(float v) { v += __shfl_xor(v, 16); v += __shfl_xor(v, 32); return v; }
; #define LAS __attribute__((address_space(3)))
; #define SCHED_FENCE() __builtin_amdgcn_sched_barrier(0)
; #define NA_ISSUE(seq_, slot_) do { _Pragma("unroll") for (int j = 0; j < 4; ++j) st[slot_][j] = bld<u32x4>(R, co, ((seq_) < 8 ? (unsigned)WS_KB + rowb + (unsigned)((seq_) * 131072) : OFF_VT + rowb + (unsigned)(((seq_) - 8) * 131072)) + (unsigned)j * 8192u); } while (0)
; __device__ __forceinline__ void na_attn_block(LAS unsigned char* lds, rsrc_t R, int l, int bx, int G, int tid, int lane, int wave) {
;     ...
;         const int hp = u & 3, r = (u >> 2) & 127, b = u >> 9, h = 2 * hp + hsel;
;         int start = r - 4; start = start < 0 ? 0 : (start > 120 ? 120 : start);
;         const unsigned rowb = (unsigned)(((b * 128 + start) * 8 + 2 * hp) * 16384);
;         u32x4 st[3][4];
;     ...
;         u32x4 qraw[4]; float s0, s1;
;         { const unsigned q_off = OFF_PROJ + (unsigned)((b * SEQ + r * 64 + 16 * qg) * PROJ_W + h * HD) * 2u;
; #pragma unroll
;           for (int ks = 0; ks < 4; ++ks) qraw[ks] = bld<u32x4>(R, qo, q_off + 64 * ks);
;           const int hs = wave & 1, a0 = wave >> 1;
;           const unsigned sso = OFF_SS + (unsigned)(SS_H + (size_t)(l * 20 + 2 * hp + hs) * NTOK + b * SEQ + (start + a0) * 64) * 4u;
;           s0 = bld<float>(R, (unsigned)(lane * 4), sso); s1 = bld<float>(R, (unsigned)(lane * 4), sso + 4u * 64u * 4u); }
;         SCHED_FENCE();
;         NA_ISSUE(0, 0); NA_ISSUE(1, 1); NA_ISSUE(2, 2);
;         SCHED_FENCE();
;         *(LAS float*)(lds + NA_SSK + tid * 4) = __builtin_amdgcn_rsqf(s0 * (1.f / HD) + EPS); *(LAS float*)(lds + NA_SSK + (tid + 512) * 4) = __builtin_amdgcn_rsqf(s1 * (1.f / HD) + EPS);
;         bf16x8 qf[4];
;         { float qv[4][8]; float ss = 0.f;
; #pragma unroll
;           for (int ks = 0; ks < 4; ++ks)
; #pragma unroll
;               for (int j = 0; j < 4; ++j) { const unsigned w = qraw[ks][j]; qv[ks][2 * j] = __builtin_bit_cast(float, w << 16); qv[ks][2 * j + 1] = __builtin_bit_cast(float, w & 0xffff0000u); ss += qv[ks][2 * j] * qv[ks][2 * j] + qv[ks][2 * j + 1] * qv[ks][2 * j + 1]; }
;           ss = pg8::sum_fq(ss);
;           const float rq = __builtin_amdgcn_rsqf(ss * (1.f / HD) + EPS);
.LBB0_185:
	s_bfe_u32 s2, s11, 0x70002
	v_med3_u32 v250, s2, 4, v222
	s_ashr_i32 s16, s11, 9
	v_readfirstlane_b32 s15, v250
	s_add_i32 s15, s15, -4
	s_lshl_b32 s12, s16, 10
	s_lshl_b32 s13, s15, 3
	s_and_b32 s17, s10, 6
	s_add_i32 s13, s13, s12
	s_or_b32 s14, s13, s17
	s_lshl_b32 s12, s16, 13
	s_lshl_b32 s13, s2, 6
	v_readlane_b32 s3, v253, 32
	s_or_b32 s12, s13, s12
	v_readlane_b32 s13, v253, 30
	s_add_i32 s3, s17, s3
	s_or_b32 s12, s12, s13
	s_lshl_b32 s13, s3, 8
	s_mul_i32 s18, s12, 0x1800
	s_add_i32 s18, s13, s18
	s_add_i32 s18, s18, 0x14e00000
	s_or_b32 s19, s18, 64
	buffer_load_dwordx4 v[64:67], v232, s[40:43], s18 offen
	buffer_load_dwordx4 v[68:71], v232, s[40:43], s19 offen
	s_or_b32 s19, s18, 0x80
	s_or_b32 s18, s18, 0xc0
	buffer_load_dwordx4 v[84:87], v232, s[40:43], s19 offen
	buffer_load_dwordx4 v[92:95], v232, s[40:43], s18 offen
	s_add_i32 s17, s4, s17
	v_readlane_b32 s18, v253, 37
	s_add_i32 s18, s15, s18
	s_lshl_b32 s17, s17, 17
	s_lshl_b32 s16, s16, 15
	s_lshl_b32 s18, s18, 8
	s_add_i32 s16, s16, s17
	s_add_i32 s16, s16, s18
	s_add_i32 s17, s16, 0x1a0000
	s_add_i32 s16, s16, 0x1a0400
	buffer_load_dword v96, v234, s[40:43], s17 offen
	buffer_load_dword v97, v234, s[40:43], s16 offen
	s_lshl_b32 s14, s14, 14
	s_add_i32 s16, s14, 0x30e00000
	buffer_load_dwordx4 v[72:75], v208, s[40:43], s16 offen
	s_add_i32 s16, s14, 0x30e02000
	buffer_load_dwordx4 v[76:79], v208, s[40:43], s16 offen
	s_add_i32 s16, s14, 0x30e04000
	buffer_load_dwordx4 v[80:83], v208, s[40:43], s16 offen
	s_add_i32 s16, s14, 0x30e06000
	buffer_load_dwordx4 v[88:91], v208, s[40:43], s16 offen
	s_add_i32 s16, s14, 0x30e20000
	buffer_load_dwordx4 v[48:51], v208, s[40:43], s16 offen
	s_add_i32 s16, s14, 0x30e22000
	buffer_load_dwordx4 v[52:55], v208, s[40:43], s16 offen
	s_add_i32 s16, s14, 0x30e24000
	buffer_load_dwordx4 v[56:59], v208, s[40:43], s16 offen
	s_add_i32 s16, s14, 0x30e26000
	buffer_load_dwordx4 v[60:63], v208, s[40:43], s16 offen
	s_add_i32 s16, s14, 0x30e40000
	buffer_load_dwordx4 v[32:35], v208, s[40:43], s16 offen
	s_add_i32 s16, s14, 0x30e42000
	buffer_load_dwordx4 v[36:39], v208, s[40:43], s16 offen
	s_add_i32 s16, s14, 0x30e44000
	buffer_load_dwordx4 v[40:43], v208, s[40:43], s16 offen
	s_add_i32 s16, s14, 0x30e46000
	buffer_load_dwordx4 v[44:47], v208, s[40:43], s16 offen
	s_waitcnt vmcnt(12)
	v_and_b32_e32 v101, 0xffff0000, v64
	v_and_b32_e32 v103, 0xffff0000, v65
	v_lshlrev_b32_e32 v100, 16, v64
	v_mul_f32_e32 v64, v101, v101
	v_lshlrev_b32_e32 v102, 16, v65
	v_mul_f32_e32 v65, v103, v103
	v_fmac_f32_e32 v64, v100, v100
	v_fmac_f32_e32 v65, v102, v102
	v_lshlrev_b32_e32 v104, 16, v66
	v_and_b32_e32 v66, 0xffff0000, v66
	v_add_f32_e32 v64, v64, v65
	v_mul_f32_e32 v65, v66, v66
	v_fmac_f32_e32 v65, v104, v104
	v_lshlrev_b32_e32 v105, 16, v67
	v_and_b32_e32 v67, 0xffff0000, v67
	v_add_f32_e32 v64, v65, v64
	v_mul_f32_e32 v65, v67, v67
	v_fmac_f32_e32 v65, v105, v105
	v_lshlrev_b32_e32 v106, 16, v68
	v_and_b32_e32 v68, 0xffff0000, v68
	v_add_f32_e32 v64, v65, v64
	v_mul_f32_e32 v65, v68, v68
	v_fmac_f32_e32 v65, v106, v106
	v_lshlrev_b32_e32 v107, 16, v69
	v_and_b32_e32 v69, 0xffff0000, v69
	v_add_f32_e32 v64, v65, v64
	v_mul_f32_e32 v65, v69, v69
	v_fmac_f32_e32 v65, v107, v107
	v_lshlrev_b32_e32 v108, 16, v70
	v_and_b32_e32 v70, 0xffff0000, v70
	v_add_f32_e32 v64, v65, v64
	v_mul_f32_e32 v65, v70, v70
	v_fmac_f32_e32 v65, v108, v108
	v_lshlrev_b32_e32 v109, 16, v71
	v_and_b32_e32 v71, 0xffff0000, v71
	v_add_f32_e32 v64, v65, v64
	v_mul_f32_e32 v65, v71, v71
	v_fmac_f32_e32 v65, v109, v109
	v_and_b32_e32 v111, 0xffff0000, v84
	v_add_f32_e32 v64, v65, v64
	v_lshlrev_b32_e32 v110, 16, v84
	v_mul_f32_e32 v65, v111, v111
	v_fmac_f32_e32 v65, v110, v110
	v_and_b32_e32 v113, 0xffff0000, v85
	v_fmamk_f32 v96, v96, 0x3c000000, v218
	v_fmamk_f32 v97, v97, 0x3c000000, v218
	v_add_f32_e32 v64, v65, v64
	v_lshlrev_b32_e32 v112, 16, v85
	v_mul_f32_e32 v65, v113, v113
	v_rsq_f32_e32 v96, v96
	v_rsq_f32_e32 v97, v97
	v_fmac_f32_e32 v65, v112, v112
	v_and_b32_e32 v115, 0xffff0000, v86
	v_add_f32_e32 v64, v65, v64
	v_lshlrev_b32_e32 v114, 16, v86
	v_mul_f32_e32 v65, v115, v115
	v_fmac_f32_e32 v65, v114, v114
	v_and_b32_e32 v117, 0xffff0000, v87
	v_add_f32_e32 v64, v65, v64
	v_lshlrev_b32_e32 v116, 16, v87
	v_mul_f32_e32 v65, v117, v117
	ds_write2st64_b32 v246, v96, v97 offset1:8
	v_fmac_f32_e32 v65, v116, v116
	v_lshlrev_b32_e32 v97, 16, v93
	v_lshlrev_b32_e32 v96, 16, v92
	v_and_b32_e32 v93, 0xffff0000, v93
	v_and_b32_e32 v92, 0xffff0000, v92
	v_add_f32_e32 v84, v65, v64
	v_pk_mul_f32 v[64:65], v[92:93], v[92:93]
	v_lshlrev_b32_e32 v99, 16, v95
	v_pk_fma_f32 v[64:65], v[96:97], v[96:97], v[64:65]
	v_lshlrev_b32_e32 v98, 16, v94
	v_add_f32_e32 v64, v64, v84
	v_and_b32_e32 v95, 0xffff0000, v95
	v_and_b32_e32 v94, 0xffff0000, v94
	v_add_f32_e32 v84, v65, v64
	v_pk_mul_f32 v[64:65], v[94:95], v[94:95]
	v_add_u32_e32 v249, 0, v208
	v_pk_fma_f32 v[64:65], v[98:99], v[98:99], v[64:65]
	s_add_i32 s16, s14, 0x30e60000
	v_add_f32_e32 v64, v64, v84
	v_add_f32_e32 v64, v65, v64
	ds_bpermute_b32 v65, v235, v64
	s_waitcnt lgkmcnt(0)
	v_add_f32_e32 v64, v64, v65
	ds_bpermute_b32 v65, v236, v64
	s_waitcnt lgkmcnt(0)
; __device__ __forceinline__ unsigned cvt_pk_bf16(float lo, float hi) { unsigned r; asm volatile("v_cvt_pk_bf16_f32 %0, %1, %2" : "=v"(r) : "v"(lo), "v"(hi)); return r; }
; #define LAS __attribute__((address_space(3)))
; #define MFMA16(a, b, c) __builtin_amdgcn_mfma_f32_16x16x32_bf16((a), (b), (c), 0, 0, 0)
; #define SCHED_FENCE() __builtin_amdgcn_sched_barrier(0)
; #define NA_ISSUE(seq_, slot_) do { _Pragma("unroll") for (int j = 0; j < 4; ++j) st[slot_][j] = bld<u32x4>(R, co, ((seq_) < 8 ? (unsigned)WS_KB + rowb + (unsigned)((seq_) * 131072) : OFF_VT + rowb + (unsigned)(((seq_) - 8) * 131072)) + (unsigned)j * 8192u); } while (0)
; #define NA_WRITE(slot_, buf_) do { _Pragma("unroll") for (int j = 0; j < 4; ++j) *(LAS u32x4*)(lds + (buf_) * NA_BUF + j * 8192 + tid * 16) = st[slot_][j]; } while (0)
; __device__ __forceinline__ void na_attn_block(LAS unsigned char* lds, rsrc_t R, int l, int bx, int G, int tid, int lane, int wave) {
;     ...
;           for (int ks = 0; ks < 4; ++ks) { const f32x4 g0 = gq[ks][0], g1 = gq[ks][1];
;               u32x4 w; w.x = pg8::cvt_pk_bf16(qv[ks][0] * rq * g0[0], qv[ks][1] * rq * g0[1]); w.y = pg8::cvt_pk_bf16(qv[ks][2] * rq * g0[2], qv[ks][3] * rq * g0[3]);
;               w.z = pg8::cvt_pk_bf16(qv[ks][4] * rq * g1[0], qv[ks][5] * rq * g1[1]); w.w = pg8::cvt_pk_bf16(qv[ks][6] * rq * g1[2], qv[ks][7] * rq * g1[3]);
;               qf[ks] = __builtin_bit_cast(bf16x8, w); } }
;         NA_WRITE(0, 0);
;         __syncthreads();
;         f32x4 S[8][2];
; #pragma unroll
;         for (int a = 0; a < 8; ++a) {
;             NA_ISSUE(a + 3, a % 3);
;             SCHED_FENCE();
;             const int buf = (a & 1) * NA_BUF;
; #pragma unroll
;             for (int t = 0; t < 2; ++t) {
;                 f32x4 acc = (f32x4){0.f, 0.f, 0.f, 0.f};
; #pragma unroll
;                 for (int ks = 0; ks < 4; ++ks) { const bf16x8 kf = *(const LAS bf16x8*)(lds + kfb + buf + t * 4096 + ks * 512); acc = MFMA16(kf, qf[ks], acc); }
;                 const f32x4 rk = *(const LAS f32x4*)(lds + skb + a * 512 + t * 64);
;                 S[a][t] = acc * rk;
;             }
;             SCHED_FENCE();
;             NA_WRITE((a + 1) % 3, (a + 1) & 1);
;             __syncthreads();
;         }
	v_add_f32_e32 v64, v64, v65
	v_fmamk_f32 v64, v64, 0x3c000000, v218
	v_rsq_f32_e32 v118, v64
	s_nop 0
	v_mul_f32_e32 v64, v118, v100
	v_mul_f32_e32 v65, v118, v101
	v_mul_f32_e32 v64, v28, v64
	v_mul_f32_e32 v65, v29, v65
	v_cvt_pk_bf16_f32 v84, v64, v65
	v_mul_f32_e32 v64, v118, v102
	v_mul_f32_e32 v65, v118, v103
	v_mul_f32_e32 v64, v30, v64
	v_mul_f32_e32 v65, v31, v65
	v_cvt_pk_bf16_f32 v85, v64, v65
	v_mul_f32_e32 v64, v118, v104
	v_mul_f32_e32 v65, v118, v66
	v_mul_f32_e32 v64, v24, v64
	v_mul_f32_e32 v65, v25, v65
	v_cvt_pk_bf16_f32 v86, v64, v65
	v_mul_f32_e32 v64, v118, v105
	v_mul_f32_e32 v65, v118, v67
	v_mul_f32_e32 v64, v26, v64
	v_mul_f32_e32 v65, v27, v65
	v_cvt_pk_bf16_f32 v87, v64, v65
	v_mul_f32_e32 v64, v118, v106
	v_mul_f32_e32 v65, v118, v68
	v_mul_f32_e32 v64, v20, v64
	v_mul_f32_e32 v65, v21, v65
	v_cvt_pk_bf16_f32 v64, v64, v65
	v_mul_f32_e32 v65, v118, v107
	v_mul_f32_e32 v66, v118, v69
	v_mul_f32_e32 v65, v22, v65
	v_mul_f32_e32 v66, v23, v66
	v_cvt_pk_bf16_f32 v65, v65, v66
	v_mul_f32_e32 v66, v118, v108
	v_mul_f32_e32 v67, v118, v70
	v_mul_f32_e32 v66, v16, v66
	v_mul_f32_e32 v67, v17, v67
	v_cvt_pk_bf16_f32 v66, v66, v67
	v_mul_f32_e32 v67, v118, v109
	v_mul_f32_e32 v68, v118, v71
	v_mul_f32_e32 v67, v18, v67
	v_mul_f32_e32 v68, v19, v68
	v_cvt_pk_bf16_f32 v67, v67, v68
	v_mul_f32_e32 v68, v118, v110
	v_mul_f32_e32 v69, v118, v111
	v_mul_f32_e32 v68, v12, v68
	v_mul_f32_e32 v69, v13, v69
	v_cvt_pk_bf16_f32 v68, v68, v69
	v_mul_f32_e32 v69, v118, v112
	v_mul_f32_e32 v70, v118, v113
	v_mul_f32_e32 v69, v14, v69
	v_mul_f32_e32 v70, v15, v70
	v_cvt_pk_bf16_f32 v69, v69, v70
	v_mul_f32_e32 v70, v118, v114
	v_mul_f32_e32 v71, v118, v115
	v_mul_f32_e32 v70, v8, v70
	v_mul_f32_e32 v71, v9, v71
	v_cvt_pk_bf16_f32 v70, v70, v71
	v_mul_f32_e32 v71, v118, v116
	v_mul_f32_e32 v92, v118, v92
	v_mul_f32_e32 v71, v10, v71
	v_mul_f32_e32 v100, v118, v117
	v_mul_f32_e32 v96, v118, v96
	v_mul_f32_e32 v92, v5, v92
	v_mul_f32_e32 v100, v11, v100
	v_cvt_pk_bf16_f32 v71, v71, v100
	v_mul_f32_e32 v96, v4, v96
	v_cvt_pk_bf16_f32 v104, v96, v92
	v_mul_f32_e32 v92, v118, v97
	v_mul_f32_e32 v93, v118, v93
	v_mul_f32_e32 v92, v6, v92
	v_mul_f32_e32 v93, v7, v93
	v_cvt_pk_bf16_f32 v105, v92, v93
	v_mul_f32_e32 v92, v118, v98
	v_mul_f32_e32 v93, v118, v94
	v_mul_f32_e32 v92, v0, v92
	v_mul_f32_e32 v93, v1, v93
	v_cvt_pk_bf16_f32 v106, v92, v93
	v_mul_f32_e32 v92, v118, v99
	v_mul_f32_e32 v93, v118, v95
	v_mul_f32_e32 v92, v2, v92
	v_mul_f32_e32 v93, v3, v93
	v_cvt_pk_bf16_f32 v107, v92, v93
	s_waitcnt vmcnt(8)
	ds_write_b128 v249, v[72:75]
	ds_write_b128 v249, v[76:79] offset:8192
	ds_write_b128 v249, v[80:83] offset:16384
	ds_write_b128 v249, v[88:91] offset:24576
	s_waitcnt lgkmcnt(0)
	s_barrier
	buffer_load_dwordx4 v[72:75], v208, s[40:43], s16 offen
	s_add_i32 s16, s14, 0x30e62000
	buffer_load_dwordx4 v[76:79], v208, s[40:43], s16 offen
	s_add_i32 s16, s14, 0x30e64000
	buffer_load_dwordx4 v[80:83], v208, s[40:43], s16 offen
	s_add_i32 s16, s14, 0x30e66000
	buffer_load_dwordx4 v[88:91], v208, s[40:43], s16 offen
	s_nop 7
	ds_read_b128 v[210:213], v247
	ds_read_b128 v[224:227], v247 offset:512
	ds_read_b128 v[184:187], v248 offset:64
	ds_read_b128 v[228:231], v247 offset:1024
	ds_read_b128 v[96:99], v248
	s_waitcnt lgkmcnt(4)
	v_mfma_f32_16x16x32_bf16 v[92:95], v[210:213], v[84:87], 0
	ds_read_b128 v[210:213], v247 offset:1536
	s_waitcnt lgkmcnt(4)
	v_mfma_f32_16x16x32_bf16 v[92:95], v[224:227], v[64:67], v[92:95]
	ds_read_b128 v[224:227], v247 offset:4096
	s_waitcnt lgkmcnt(3)
	v_mfma_f32_16x16x32_bf16 v[92:95], v[228:231], v[68:71], v[92:95]
	ds_read_b128 v[228:231], v247 offset:4608
	s_waitcnt lgkmcnt(2)
	v_mfma_f32_16x16x32_bf16 v[92:95], v[210:213], v[104:107], v[92:95]
	ds_read_b128 v[210:213], v247 offset:5120
	s_nop 6
	v_pk_mul_f32 v[214:215], v[94:95], v[98:99]
	v_pk_mul_f32 v[216:217], v[92:93], v[96:97]
	s_waitcnt lgkmcnt(2)
	v_mfma_f32_16x16x32_bf16 v[92:95], v[224:227], v[84:87], 0
	ds_read_b128 v[224:227], v247 offset:5632
	s_waitcnt lgkmcnt(2)
	v_mfma_f32_16x16x32_bf16 v[92:95], v[228:231], v[64:67], v[92:95]
	s_waitcnt lgkmcnt(1)
	v_mfma_f32_16x16x32_bf16 v[92:95], v[210:213], v[68:71], v[92:95]
	s_waitcnt lgkmcnt(0)
	v_mfma_f32_16x16x32_bf16 v[176:179], v[224:227], v[104:107], v[92:95]
	s_nop 7
	s_nop 0
	s_add_i32 s16, s14, 0x30e80000
	s_waitcnt vmcnt(8)
	ds_write_b128 v249, v[48:51] offset:32768
	ds_write_b128 v249, v[52:55] offset:40960
	ds_write_b128 v249, v[56:59] offset:49152
	ds_write_b128 v249, v[60:63] offset:57344
	s_waitcnt lgkmcnt(0)
	s_barrier
	buffer_load_dwordx4 v[48:51], v208, s[40:43], s16 offen
	s_add_i32 s16, s14, 0x30e82000
	buffer_load_dwordx4 v[52:55], v208, s[40:43], s16 offen
	s_add_i32 s16, s14, 0x30e84000
	buffer_load_dwordx4 v[56:59], v208, s[40:43], s16 offen
	s_add_i32 s16, s14, 0x30e86000
	buffer_load_dwordx4 v[92:95], v208, s[40:43], s16 offen
	s_nop 7
	ds_read_b128 v[210:213], v247 offset:32768
	ds_read_b128 v[224:227], v247 offset:33280
	ds_read_b128 v[228:231], v247 offset:33792
	ds_read_b128 v[168:171], v248 offset:512
	ds_read_b128 v[180:183], v248 offset:576
	s_waitcnt lgkmcnt(4)
	v_mfma_f32_16x16x32_bf16 v[60:63], v[210:213], v[84:87], 0
	ds_read_b128 v[210:213], v247 offset:34304
	s_waitcnt lgkmcnt(4)
	v_mfma_f32_16x16x32_bf16 v[60:63], v[224:227], v[64:67], v[60:63]
	ds_read_b128 v[224:227], v247 offset:36864
	s_waitcnt lgkmcnt(4)
	v_mfma_f32_16x16x32_bf16 v[60:63], v[228:231], v[68:71], v[60:63]
	ds_read_b128 v[228:231], v247 offset:37376
	s_waitcnt lgkmcnt(2)
	v_mfma_f32_16x16x32_bf16 v[164:167], v[210:213], v[104:107], v[60:63]
	ds_read_b128 v[210:213], v247 offset:37888
	s_waitcnt lgkmcnt(2)
	v_mfma_f32_16x16x32_bf16 v[60:63], v[224:227], v[84:87], 0
	ds_read_b128 v[224:227], v247 offset:38400
	s_waitcnt lgkmcnt(2)
	v_mfma_f32_16x16x32_bf16 v[60:63], v[228:231], v[64:67], v[60:63]
	s_waitcnt lgkmcnt(1)
	v_mfma_f32_16x16x32_bf16 v[60:63], v[210:213], v[68:71], v[60:63]
	s_waitcnt lgkmcnt(0)
	v_mfma_f32_16x16x32_bf16 v[172:175], v[224:227], v[104:107], v[60:63]
	s_nop 7
	s_nop 0
	s_add_i32 s16, s14, 0x30ea0000
	s_waitcnt vmcnt(8)
	ds_write_b128 v249, v[32:35]
	ds_write_b128 v249, v[36:39] offset:8192
	ds_write_b128 v249, v[40:43] offset:16384
	ds_write_b128 v249, v[44:47] offset:24576
	s_waitcnt lgkmcnt(0)
	s_barrier
; #define LAS __attribute__((address_space(3)))
; #define MFMA16(a, b, c) __builtin_amdgcn_mfma_f32_16x16x32_bf16((a), (b), (c), 0, 0, 0)
; #define SCHED_FENCE() __builtin_amdgcn_sched_barrier(0)
; #define NA_ISSUE(seq_, slot_) do { _Pragma("unroll") for (int j = 0; j < 4; ++j) st[slot_][j] = bld<u32x4>(R, co, ((seq_) < 8 ? (unsigned)WS_KB + rowb + (unsigned)((seq_) * 131072) : OFF_VT + rowb + (unsigned)(((seq_) - 8) * 131072)) + (unsigned)j * 8192u); } while (0)
; #define NA_WRITE(slot_, buf_) do { _Pragma("unroll") for (int j = 0; j < 4; ++j) *(LAS u32x4*)(lds + (buf_) * NA_BUF + j * 8192 + tid * 16) = st[slot_][j]; } while (0)
; __device__ __forceinline__ void na_attn_block(LAS unsigned char* lds, rsrc_t R, int l, int bx, int G, int tid, int lane, int wave) {
;     ...
; #pragma unroll
;         for (int a = 0; a < 8; ++a) {
;             NA_ISSUE(a + 3, a % 3);
;             SCHED_FENCE();
;             const int buf = (a & 1) * NA_BUF;
; #pragma unroll
;             for (int t = 0; t < 2; ++t) {
;                 f32x4 acc = (f32x4){0.f, 0.f, 0.f, 0.f};
; #pragma unroll
;                 for (int ks = 0; ks < 4; ++ks) { const bf16x8 kf = *(const LAS bf16x8*)(lds + kfb + buf + t * 4096 + ks * 512); acc = MFMA16(kf, qf[ks], acc); }
;                 const f32x4 rk = *(const LAS f32x4*)(lds + skb + a * 512 + t * 64);
;                 S[a][t] = acc * rk;
;             }
;             SCHED_FENCE();
;             NA_WRITE((a + 1) % 3, (a + 1) & 1);
;             __syncthreads();
;         }
	buffer_load_dwordx4 v[32:35], v208, s[40:43], s16 offen
	s_add_i32 s16, s14, 0x30ea2000
	buffer_load_dwordx4 v[40:43], v208, s[40:43], s16 offen
	s_add_i32 s16, s14, 0x30ea4000
	buffer_load_dwordx4 v[60:63], v208, s[40:43], s16 offen
	s_add_i32 s16, s14, 0x30ea6000
	buffer_load_dwordx4 v[96:99], v208, s[40:43], s16 offen
	s_nop 7
	ds_read_b128 v[210:213], v247
	ds_read_b128 v[224:227], v247 offset:512
	ds_read_b128 v[228:231], v247 offset:1024
	ds_read_b128 v[152:155], v248 offset:1024
	ds_read_b128 v[160:163], v248 offset:1088
	s_waitcnt lgkmcnt(4)
	v_mfma_f32_16x16x32_bf16 v[36:39], v[210:213], v[84:87], 0
	ds_read_b128 v[210:213], v247 offset:1536
	s_waitcnt lgkmcnt(4)
	v_mfma_f32_16x16x32_bf16 v[36:39], v[224:227], v[64:67], v[36:39]
	ds_read_b128 v[224:227], v247 offset:4096
	s_waitcnt lgkmcnt(4)
	v_mfma_f32_16x16x32_bf16 v[36:39], v[228:231], v[68:71], v[36:39]
	ds_read_b128 v[228:231], v247 offset:4608
	s_waitcnt lgkmcnt(2)
	v_mfma_f32_16x16x32_bf16 v[148:151], v[210:213], v[104:107], v[36:39]
	ds_read_b128 v[210:213], v247 offset:5120
	s_waitcnt lgkmcnt(2)
	v_mfma_f32_16x16x32_bf16 v[36:39], v[224:227], v[84:87], 0
	ds_read_b128 v[224:227], v247 offset:5632
	s_waitcnt lgkmcnt(2)
	v_mfma_f32_16x16x32_bf16 v[36:39], v[228:231], v[64:67], v[36:39]
	s_waitcnt lgkmcnt(1)
	v_mfma_f32_16x16x32_bf16 v[36:39], v[210:213], v[68:71], v[36:39]
	s_waitcnt lgkmcnt(0)
	v_mfma_f32_16x16x32_bf16 v[156:159], v[224:227], v[104:107], v[36:39]
	s_nop 7
	s_nop 0
	s_add_i32 s16, s14, 0x30ec0000
	s_waitcnt vmcnt(11)
	ds_write_b128 v249, v[72:75] offset:32768
	s_waitcnt vmcnt(10)
	ds_write_b128 v249, v[76:79] offset:40960
	s_waitcnt vmcnt(9)
	ds_write_b128 v249, v[80:83] offset:49152
	s_waitcnt vmcnt(8)
	ds_write_b128 v249, v[88:91] offset:57344
	s_waitcnt lgkmcnt(0)
	s_barrier
	buffer_load_dwordx4 v[36:39], v208, s[40:43], s16 offen
	s_add_i32 s16, s14, 0x30ec2000
	buffer_load_dwordx4 v[44:47], v208, s[40:43], s16 offen
	s_add_i32 s16, s14, 0x30ec4000
	buffer_load_dwordx4 v[72:75], v208, s[40:43], s16 offen
	s_add_i32 s16, s14, 0x30ec6000
	buffer_load_dwordx4 v[76:79], v208, s[40:43], s16 offen
	s_nop 7
	ds_read_b128 v[210:213], v247 offset:32768
	ds_read_b128 v[224:227], v247 offset:33280
	ds_read_b128 v[228:231], v247 offset:33792
	ds_read_b128 v[132:135], v248 offset:1536
	ds_read_b128 v[144:147], v248 offset:1600
	s_waitcnt lgkmcnt(4)
	v_mfma_f32_16x16x32_bf16 v[80:83], v[210:213], v[84:87], 0
	ds_read_b128 v[210:213], v247 offset:34304
	s_waitcnt lgkmcnt(4)
	v_mfma_f32_16x16x32_bf16 v[80:83], v[224:227], v[64:67], v[80:83]
	ds_read_b128 v[224:227], v247 offset:36864
	s_waitcnt lgkmcnt(4)
	v_mfma_f32_16x16x32_bf16 v[80:83], v[228:231], v[68:71], v[80:83]
	ds_read_b128 v[228:231], v247 offset:37376
	s_waitcnt lgkmcnt(2)
	v_mfma_f32_16x16x32_bf16 v[128:131], v[210:213], v[104:107], v[80:83]
	ds_read_b128 v[210:213], v247 offset:37888
	s_waitcnt lgkmcnt(2)
	v_mfma_f32_16x16x32_bf16 v[80:83], v[224:227], v[84:87], 0
	ds_read_b128 v[224:227], v247 offset:38400
	s_waitcnt lgkmcnt(2)
	v_mfma_f32_16x16x32_bf16 v[80:83], v[228:231], v[64:67], v[80:83]
	s_waitcnt lgkmcnt(1)
	v_mfma_f32_16x16x32_bf16 v[80:83], v[210:213], v[68:71], v[80:83]
	s_waitcnt lgkmcnt(0)
	v_mfma_f32_16x16x32_bf16 v[136:139], v[224:227], v[104:107], v[80:83]
	s_nop 7
	s_nop 0
	s_add_i32 s16, s14, 0x30ee0000
	s_waitcnt vmcnt(11)
	ds_write_b128 v249, v[48:51]
	s_waitcnt vmcnt(10)
	ds_write_b128 v249, v[52:55] offset:8192
	s_waitcnt vmcnt(9)
	ds_write_b128 v249, v[56:59] offset:16384
	s_waitcnt vmcnt(8)
	ds_write_b128 v249, v[92:95] offset:24576
	s_waitcnt lgkmcnt(0)
	s_barrier
	buffer_load_dwordx4 v[48:51], v208, s[40:43], s16 offen
	s_add_i32 s16, s14, 0x30ee2000
	buffer_load_dwordx4 v[52:55], v208, s[40:43], s16 offen
	s_add_i32 s16, s14, 0x30ee4000
	buffer_load_dwordx4 v[140:143], v208, s[40:43], s16 offen
	s_add_i32 s16, s14, 0x30ee6000
	buffer_load_dwordx4 v[192:195], v208, s[40:43], s16 offen
	s_nop 7
	ds_read_b128 v[210:213], v247
	ds_read_b128 v[224:227], v247 offset:512
	ds_read_b128 v[228:231], v247 offset:1024
	ds_read_b128 v[120:123], v248 offset:2048
	ds_read_b128 v[124:127], v248 offset:2112
	s_waitcnt lgkmcnt(4)
	v_mfma_f32_16x16x32_bf16 v[56:59], v[210:213], v[84:87], 0
	ds_read_b128 v[210:213], v247 offset:1536
	s_waitcnt lgkmcnt(4)
	v_mfma_f32_16x16x32_bf16 v[56:59], v[224:227], v[64:67], v[56:59]
	ds_read_b128 v[224:227], v247 offset:4096
	s_waitcnt lgkmcnt(4)
	v_mfma_f32_16x16x32_bf16 v[56:59], v[228:231], v[68:71], v[56:59]
	ds_read_b128 v[228:231], v247 offset:4608
	s_waitcnt lgkmcnt(2)
	v_mfma_f32_16x16x32_bf16 v[116:119], v[210:213], v[104:107], v[56:59]
	ds_read_b128 v[210:213], v247 offset:5120
	s_waitcnt lgkmcnt(2)
	v_mfma_f32_16x16x32_bf16 v[56:59], v[224:227], v[84:87], 0
	ds_read_b128 v[224:227], v247 offset:5632
	s_waitcnt lgkmcnt(2)
	v_mfma_f32_16x16x32_bf16 v[56:59], v[228:231], v[64:67], v[56:59]
	s_waitcnt lgkmcnt(1)
	v_mfma_f32_16x16x32_bf16 v[56:59], v[210:213], v[68:71], v[56:59]
	s_waitcnt lgkmcnt(0)
	v_mfma_f32_16x16x32_bf16 v[112:115], v[224:227], v[104:107], v[56:59]
	s_nop 7
	s_nop 0
	s_add_i32 s16, s14, 0x20e00000
	s_waitcnt vmcnt(11)
	ds_write_b128 v249, v[32:35] offset:32768
	s_waitcnt vmcnt(10)
	ds_write_b128 v249, v[40:43] offset:40960
	s_waitcnt vmcnt(9)
	ds_write_b128 v249, v[60:63] offset:49152
	s_waitcnt vmcnt(8)
	ds_write_b128 v249, v[96:99] offset:57344
	s_waitcnt lgkmcnt(0)
	s_barrier
; #define LAS __attribute__((address_space(3)))
; #define MFMA16(a, b, c) __builtin_amdgcn_mfma_f32_16x16x32_bf16((a), (b), (c), 0, 0, 0)
; #define SCHED_FENCE() __builtin_amdgcn_sched_barrier(0)
; #define NA_ISSUE(seq_, slot_) do { _Pragma("unroll") for (int j = 0; j < 4; ++j) st[slot_][j] = bld<u32x4>(R, co, ((seq_) < 8 ? (unsigned)WS_KB + rowb + (unsigned)((seq_) * 131072) : OFF_VT + rowb + (unsigned)(((seq_) - 8) * 131072)) + (unsigned)j * 8192u); } while (0)
; #define NA_WRITE(slot_, buf_) do { _Pragma("unroll") for (int j = 0; j < 4; ++j) *(LAS u32x4*)(lds + (buf_) * NA_BUF + j * 8192 + tid * 16) = st[slot_][j]; } while (0)
; __device__ __forceinline__ void na_attn_block(LAS unsigned char* lds, rsrc_t R, int l, int bx, int G, int tid, int lane, int wave) {
;     ...
; #pragma unroll
;         for (int a = 0; a < 8; ++a) {
;             NA_ISSUE(a + 3, a % 3);
;             SCHED_FENCE();
;             const int buf = (a & 1) * NA_BUF;
; #pragma unroll
;             for (int t = 0; t < 2; ++t) {
;                 f32x4 acc = (f32x4){0.f, 0.f, 0.f, 0.f};
; #pragma unroll
;                 for (int ks = 0; ks < 4; ++ks) { const bf16x8 kf = *(const LAS bf16x8*)(lds + kfb + buf + t * 4096 + ks * 512); acc = MFMA16(kf, qf[ks], acc); }
;                 const f32x4 rk = *(const LAS f32x4*)(lds + skb + a * 512 + t * 64);
;                 S[a][t] = acc * rk;
;             }
;             SCHED_FENCE();
;             NA_WRITE((a + 1) % 3, (a + 1) & 1);
;             __syncthreads();
;         }
;         { const int rowidx0 = start - r + 7;
; #pragma unroll
;           for (int a = 0; a < 8; ++a)
; #pragma unroll
;               for (int q = 0; q < 8; ++q) { const int kcol = kc0 + 16 * (q >> 2) + 4 * kq + (q & 3); const bool valid = (kcol >= cs) && (kcol < cs + 16);
;                   int ci = kcol - qcol + 15; ci = ci < 0 ? 0 : (ci > 30 ? 30 : ci);
;                   const float bias = *(const LAS float*)(lds + NA_RPB + ((h * 15 + rowidx0 + a) * 31 + ci) * 4);
	buffer_load_dwordx4 v[188:191], v208, s[40:43], s16 offen
	s_add_i32 s16, s14, 0x20e02000
	buffer_load_dwordx4 v[196:199], v208, s[40:43], s16 offen
	s_add_i32 s16, s14, 0x20e04000
	buffer_load_dwordx4 v[200:203], v208, s[40:43], s16 offen
	s_add_i32 s16, s14, 0x20e06000
	buffer_load_dwordx4 v[204:207], v208, s[40:43], s16 offen
	s_nop 7
	ds_read_b128 v[210:213], v247 offset:32768
	ds_read_b128 v[224:227], v247 offset:33280
	ds_read_b128 v[228:231], v247 offset:33792
	ds_read_b128 v[96:99], v248 offset:2560
	ds_read_b128 v[108:111], v248 offset:2624
	s_waitcnt lgkmcnt(4)
	v_mfma_f32_16x16x32_bf16 v[32:35], v[210:213], v[84:87], 0
	ds_read_b128 v[210:213], v247 offset:34304
	s_waitcnt lgkmcnt(4)
	v_mfma_f32_16x16x32_bf16 v[32:35], v[224:227], v[64:67], v[32:35]
	ds_read_b128 v[224:227], v247 offset:36864
	s_waitcnt lgkmcnt(4)
	v_mfma_f32_16x16x32_bf16 v[32:35], v[228:231], v[68:71], v[32:35]
	ds_read_b128 v[228:231], v247 offset:37376
	s_waitcnt lgkmcnt(2)
	v_mfma_f32_16x16x32_bf16 v[92:95], v[210:213], v[104:107], v[32:35]
	ds_read_b128 v[210:213], v247 offset:37888
	s_waitcnt lgkmcnt(2)
	v_mfma_f32_16x16x32_bf16 v[32:35], v[224:227], v[84:87], 0
	ds_read_b128 v[224:227], v247 offset:38400
	s_waitcnt lgkmcnt(2)
	v_mfma_f32_16x16x32_bf16 v[32:35], v[228:231], v[64:67], v[32:35]
	s_waitcnt lgkmcnt(1)
	v_mfma_f32_16x16x32_bf16 v[32:35], v[210:213], v[68:71], v[32:35]
	s_waitcnt lgkmcnt(0)
	v_mfma_f32_16x16x32_bf16 v[100:103], v[224:227], v[104:107], v[32:35]
	s_nop 7
	s_nop 0
	s_add_i32 s16, s14, 0x20e20000
	s_waitcnt vmcnt(11)
	ds_write_b128 v249, v[36:39]
	s_waitcnt vmcnt(10)
	ds_write_b128 v249, v[44:47] offset:8192
	s_waitcnt vmcnt(9)
	ds_write_b128 v249, v[72:75] offset:16384
	s_waitcnt vmcnt(8)
	ds_write_b128 v249, v[76:79] offset:24576
	s_waitcnt lgkmcnt(0)
	s_barrier
	buffer_load_dwordx4 v[32:35], v208, s[40:43], s16 offen
	s_add_i32 s16, s14, 0x20e22000
	buffer_load_dwordx4 v[40:43], v208, s[40:43], s16 offen
	s_add_i32 s16, s14, 0x20e24000
	buffer_load_dwordx4 v[44:47], v208, s[40:43], s16 offen
	s_add_i32 s16, s14, 0x20e26000
	buffer_load_dwordx4 v[56:59], v208, s[40:43], s16 offen
	s_nop 7
	ds_read_b128 v[210:213], v247
	ds_read_b128 v[224:227], v247 offset:512
	ds_read_b128 v[228:231], v247 offset:1024
	ds_read_b128 v[76:79], v248 offset:3072
	ds_read_b128 v[88:91], v248 offset:3136
	s_waitcnt lgkmcnt(4)
	v_mfma_f32_16x16x32_bf16 v[36:39], v[210:213], v[84:87], 0
	ds_read_b128 v[210:213], v247 offset:1536
	s_waitcnt lgkmcnt(4)
	v_mfma_f32_16x16x32_bf16 v[36:39], v[224:227], v[64:67], v[36:39]
	ds_read_b128 v[224:227], v247 offset:4096
	s_waitcnt lgkmcnt(4)
	v_mfma_f32_16x16x32_bf16 v[36:39], v[228:231], v[68:71], v[36:39]
	ds_read_b128 v[228:231], v247 offset:4608
	s_waitcnt lgkmcnt(2)
	v_mfma_f32_16x16x32_bf16 v[72:75], v[210:213], v[104:107], v[36:39]
	ds_read_b128 v[210:213], v247 offset:5120
	s_waitcnt lgkmcnt(2)
	v_mfma_f32_16x16x32_bf16 v[36:39], v[224:227], v[84:87], 0
	ds_read_b128 v[224:227], v247 offset:5632
	s_waitcnt lgkmcnt(2)
	v_mfma_f32_16x16x32_bf16 v[36:39], v[228:231], v[64:67], v[36:39]
	s_waitcnt lgkmcnt(1)
	v_mfma_f32_16x16x32_bf16 v[36:39], v[210:213], v[68:71], v[36:39]
	s_waitcnt lgkmcnt(0)
	v_mfma_f32_16x16x32_bf16 v[80:83], v[224:227], v[104:107], v[36:39]
	s_nop 7
	s_nop 0
	s_add_i32 s16, s14, 0x20e40000
	s_waitcnt vmcnt(11)
	ds_write_b128 v249, v[48:51] offset:32768
	s_waitcnt vmcnt(10)
	ds_write_b128 v249, v[52:55] offset:40960
	s_waitcnt vmcnt(9)
	ds_write_b128 v249, v[140:143] offset:49152
	s_waitcnt vmcnt(8)
	ds_write_b128 v249, v[192:195] offset:57344
	s_waitcnt lgkmcnt(0)
	s_barrier
	buffer_load_dwordx4 v[36:39], v208, s[40:43], s16 offen
	s_add_i32 s16, s14, 0x20e42000
	buffer_load_dwordx4 v[48:51], v208, s[40:43], s16 offen
	s_add_i32 s16, s14, 0x20e44000
	buffer_load_dwordx4 v[52:55], v208, s[40:43], s16 offen
	s_add_i32 s16, s14, 0x20e46000
	buffer_load_dwordx4 v[60:63], v208, s[40:43], s16 offen
	s_nop 7
	ds_read_b128 v[210:213], v247 offset:32768
	ds_read_b128 v[224:227], v247 offset:36864
	ds_read_b128 v[228:231], v247 offset:33280
	s_waitcnt lgkmcnt(2)
	v_mfma_f32_16x16x32_bf16 v[140:143], v[210:213], v[84:87], 0
	ds_read_b128 v[210:213], v247 offset:33792
	s_waitcnt lgkmcnt(2)
	v_mfma_f32_16x16x32_bf16 v[192:195], v[224:227], v[84:87], 0
	ds_read_b128 v[224:227], v247 offset:34304
	s_waitcnt lgkmcnt(2)
	v_mfma_f32_16x16x32_bf16 v[84:87], v[228:231], v[64:67], v[140:143]
	ds_read_b128 v[228:231], v247 offset:37376
	s_nop 0
	ds_read_b128 v[140:143], v248 offset:3584
	s_waitcnt lgkmcnt(3)
	v_mfma_f32_16x16x32_bf16 v[84:87], v[210:213], v[68:71], v[84:87]
	ds_read_b128 v[210:213], v247 offset:37888
	s_waitcnt lgkmcnt(3)
	v_mfma_f32_16x16x32_bf16 v[84:87], v[224:227], v[104:107], v[84:87]
	ds_read_b128 v[224:227], v247 offset:38400
	s_waitcnt lgkmcnt(3)
	v_mfma_f32_16x16x32_bf16 v[64:67], v[228:231], v[64:67], v[192:195]
	s_waitcnt lgkmcnt(1)
	v_mfma_f32_16x16x32_bf16 v[68:71], v[210:213], v[68:71], v[64:67]
	s_nop 5
	ds_read_b128 v[64:67], v248 offset:3648
	s_waitcnt lgkmcnt(1)
	v_mfma_f32_16x16x32_bf16 v[68:71], v[224:227], v[104:107], v[68:71]
	s_waitcnt lgkmcnt(0)
	s_nop 6
	s_nop 0
	s_mul_i32 s3, s3, 15
	s_sub_i32 s16, s3, s2
	s_add_i32 s16, s16, 7
	s_add_i32 s15, s16, s15
	s_mul_i32 s15, s15, 31
	s_waitcnt vmcnt(11)
	ds_write_b128 v249, v[188:191]
	s_waitcnt vmcnt(10)
	ds_write_b128 v249, v[196:199] offset:8192
	s_waitcnt vmcnt(9)
	ds_write_b128 v249, v[200:203] offset:16384
	s_waitcnt vmcnt(8)
	ds_write_b128 v249, v[204:207] offset:24576
	s_add_i32 s17, s15, 15
	v_mov_b32_e32 v188, 0xf149f2ca
	v_mov_b32_e32 v189, 0xf149f2ca
	s_waitcnt lgkmcnt(0)
	s_barrier
; #define LAS __attribute__((address_space(3)))
; __device__ __forceinline__ void na_attn_block(LAS unsigned char* lds, rsrc_t R, int l, int bx, int G, int tid, int lane, int wave) {
;     ...
;         { const int rowidx0 = start - r + 7;
; #pragma unroll
;           for (int a = 0; a < 8; ++a)
; #pragma unroll
;               for (int q = 0; q < 8; ++q) { const int kcol = kc0 + 16 * (q >> 2) + 4 * kq + (q & 3); const bool valid = (kcol >= cs) && (kcol < cs + 16);
;                   int ci = kcol - qcol + 15; ci = ci < 0 ? 0 : (ci > 30 ? 30 : ci);
;                   const float bias = *(const LAS float*)(lds + NA_RPB + ((h * 15 + rowidx0 + a) * 31 + ci) * 4);
;                   S[a][q >> 2][q & 3] = valid ? S[a][q >> 2][q & 3] + bias : -1e30f; } }
	v_add_u32_e32 v210, s17, v238
	v_lshl_add_u32 v210, v210, 2, 0
	v_add_u32_e32 v210, 0x11000, v210
	ds_read_b32 v210, v210
	v_add_u32_e32 v211, s17, v239
	v_lshl_add_u32 v211, v211, 2, 0
	v_add_u32_e32 v211, 0x11000, v211
	ds_read_b32 v211, v211
	v_add_u32_e32 v212, s17, v240
	v_lshl_add_u32 v212, v212, 2, 0
	v_add_u32_e32 v212, 0x11000, v212
	ds_read_b32 v212, v212
	v_add_u32_e32 v213, s17, v241
	v_lshl_add_u32 v213, v213, 2, 0
	v_add_u32_e32 v213, 0x11000, v213
	ds_read_b32 v213, v213
	s_waitcnt lgkmcnt(3)
	v_add_f32_e32 v210, v216, v210
	v_cndmask_b32_e64 v189, v189, v210, s[6:7]
	s_waitcnt lgkmcnt(2)
	v_add_f32_e32 v211, v217, v211
	v_cndmask_b32_e64 v188, v188, v211, s[22:23]
	v_mov_b32_e32 v190, 0xf149f2ca
	v_mov_b32_e32 v191, 0xf149f2ca
	s_waitcnt lgkmcnt(1)
	v_add_f32_e32 v212, v214, v212
	v_cndmask_b32_e64 v191, v191, v212, s[28:29]
	s_waitcnt lgkmcnt(0)
	v_add_f32_e32 v213, v215, v213
	v_cndmask_b32_e64 v190, v190, v213, s[30:31]
	v_pk_mul_f32 v[104:105], v[178:179], v[186:187]
	v_pk_mul_f32 v[106:107], v[176:177], v[184:185]
	v_mov_b32_e32 v176, 0xf149f2ca
	v_mov_b32_e32 v177, 0xf149f2ca
	v_add_u32_e32 v210, s17, v242
	v_lshl_add_u32 v210, v210, 2, 0
	v_add_u32_e32 v210, 0x11000, v210
	ds_read_b32 v210, v210
	v_add_u32_e32 v211, s17, v243
	v_lshl_add_u32 v211, v211, 2, 0
	v_add_u32_e32 v211, 0x11000, v211
	ds_read_b32 v211, v211
	v_add_u32_e32 v212, s17, v244
	v_lshl_add_u32 v212, v212, 2, 0
	v_add_u32_e32 v212, 0x11000, v212
	ds_read_b32 v212, v212
	v_add_u32_e32 v213, s17, v245
	v_lshl_add_u32 v213, v213, 2, 0
	v_add_u32_e32 v213, 0x11000, v213
	ds_read_b32 v213, v213
	s_waitcnt lgkmcnt(3)
	v_add_f32_e32 v210, v106, v210
	v_cndmask_b32_e64 v177, v177, v210, s[36:37]
	s_waitcnt lgkmcnt(2)
	v_add_f32_e32 v211, v107, v211
	v_cndmask_b32_e64 v176, v176, v211, s[38:39]
	v_mov_b32_e32 v178, 0xf149f2ca
	v_mov_b32_e32 v179, 0xf149f2ca
	s_waitcnt lgkmcnt(1)
	v_add_f32_e32 v212, v104, v212
	v_cndmask_b32_e64 v179, v179, v212, s[44:45]
	s_waitcnt lgkmcnt(0)
	v_add_f32_e32 v213, v105, v213
	v_cndmask_b32_e64 v178, v178, v213, s[0:1]
	v_pk_mul_f32 v[104:105], v[166:167], v[170:171]
	v_pk_mul_f32 v[106:107], v[164:165], v[168:169]
	s_add_i32 s17, s15, 46
	v_mov_b32_e32 v164, 0xf149f2ca
	v_mov_b32_e32 v165, 0xf149f2ca
	v_add_u32_e32 v210, s17, v238
	v_lshl_add_u32 v210, v210, 2, 0
	v_add_u32_e32 v210, 0x11000, v210
	ds_read_b32 v210, v210
	v_add_u32_e32 v211, s17, v239
	v_lshl_add_u32 v211, v211, 2, 0
	v_add_u32_e32 v211, 0x11000, v211
	ds_read_b32 v211, v211
	v_add_u32_e32 v212, s17, v240
	v_lshl_add_u32 v212, v212, 2, 0
	v_add_u32_e32 v212, 0x11000, v212
	ds_read_b32 v212, v212
	v_add_u32_e32 v213, s17, v241
	v_lshl_add_u32 v213, v213, 2, 0
	v_add_u32_e32 v213, 0x11000, v213
	ds_read_b32 v213, v213
	s_waitcnt lgkmcnt(3)
	v_add_f32_e32 v210, v106, v210
	v_cndmask_b32_e64 v165, v165, v210, s[6:7]
	s_waitcnt lgkmcnt(2)
	v_add_f32_e32 v211, v107, v211
	v_cndmask_b32_e64 v164, v164, v211, s[22:23]
	v_mov_b32_e32 v166, 0xf149f2ca
	v_mov_b32_e32 v167, 0xf149f2ca
	s_waitcnt lgkmcnt(1)
	v_add_f32_e32 v212, v104, v212
	v_cndmask_b32_e64 v167, v167, v212, s[28:29]
	s_waitcnt lgkmcnt(0)
	v_add_f32_e32 v213, v105, v213
	v_cndmask_b32_e64 v166, v166, v213, s[30:31]
	v_pk_mul_f32 v[104:105], v[174:175], v[182:183]
	v_pk_mul_f32 v[106:107], v[172:173], v[180:181]
	v_mov_b32_e32 v168, 0xf149f2ca
	v_mov_b32_e32 v169, 0xf149f2ca
	v_add_u32_e32 v210, s17, v242
	v_lshl_add_u32 v210, v210, 2, 0
	v_add_u32_e32 v210, 0x11000, v210
	ds_read_b32 v210, v210
	v_add_u32_e32 v211, s17, v243
	v_lshl_add_u32 v211, v211, 2, 0
	v_add_u32_e32 v211, 0x11000, v211
	ds_read_b32 v211, v211
	v_add_u32_e32 v212, s17, v244
	v_lshl_add_u32 v212, v212, 2, 0
	v_add_u32_e32 v212, 0x11000, v212
	ds_read_b32 v212, v212
	v_add_u32_e32 v213, s17, v245
	v_lshl_add_u32 v213, v213, 2, 0
	v_add_u32_e32 v213, 0x11000, v213
	ds_read_b32 v213, v213
	s_waitcnt lgkmcnt(3)
	v_add_f32_e32 v210, v106, v210
	v_cndmask_b32_e64 v169, v169, v210, s[36:37]
	s_waitcnt lgkmcnt(2)
	v_add_f32_e32 v211, v107, v211
	v_cndmask_b32_e64 v168, v168, v211, s[38:39]
	v_mov_b32_e32 v170, 0xf149f2ca
	v_mov_b32_e32 v171, 0xf149f2ca
	s_waitcnt lgkmcnt(1)
	v_add_f32_e32 v212, v104, v212
	v_cndmask_b32_e64 v171, v171, v212, s[44:45]
	s_waitcnt lgkmcnt(0)
	v_add_f32_e32 v213, v105, v213
	v_cndmask_b32_e64 v170, v170, v213, s[0:1]
	v_pk_mul_f32 v[104:105], v[150:151], v[154:155]
	v_pk_mul_f32 v[106:107], v[148:149], v[152:153]
	s_add_i32 s17, s15, 0x4d
	v_mov_b32_e32 v148, 0xf149f2ca
	v_mov_b32_e32 v149, 0xf149f2ca
	v_add_u32_e32 v210, s17, v238
	v_lshl_add_u32 v210, v210, 2, 0
	v_add_u32_e32 v210, 0x11000, v210
	ds_read_b32 v210, v210
	v_add_u32_e32 v211, s17, v239
	v_lshl_add_u32 v211, v211, 2, 0
	v_add_u32_e32 v211, 0x11000, v211
	ds_read_b32 v211, v211
	v_add_u32_e32 v212, s17, v240
	v_lshl_add_u32 v212, v212, 2, 0
	v_add_u32_e32 v212, 0x11000, v212
	ds_read_b32 v212, v212
	v_add_u32_e32 v213, s17, v241
	v_lshl_add_u32 v213, v213, 2, 0
	v_add_u32_e32 v213, 0x11000, v213
	ds_read_b32 v213, v213
	s_waitcnt lgkmcnt(3)
	v_add_f32_e32 v210, v106, v210
	v_cndmask_b32_e64 v149, v149, v210, s[6:7]
	s_waitcnt lgkmcnt(2)
	v_add_f32_e32 v211, v107, v211
	v_cndmask_b32_e64 v148, v148, v211, s[22:23]
	v_mov_b32_e32 v150, 0xf149f2ca
	v_mov_b32_e32 v151, 0xf149f2ca
	s_waitcnt lgkmcnt(1)
	v_add_f32_e32 v212, v104, v212
	v_cndmask_b32_e64 v151, v151, v212, s[28:29]
	s_waitcnt lgkmcnt(0)
; #define LAS __attribute__((address_space(3)))
; __device__ __forceinline__ void na_attn_block(LAS unsigned char* lds, rsrc_t R, int l, int bx, int G, int tid, int lane, int wave) {
;     ...
;         { const int rowidx0 = start - r + 7;
; #pragma unroll
;           for (int a = 0; a < 8; ++a)
; #pragma unroll
;               for (int q = 0; q < 8; ++q) { const int kcol = kc0 + 16 * (q >> 2) + 4 * kq + (q & 3); const bool valid = (kcol >= cs) && (kcol < cs + 16);
;                   int ci = kcol - qcol + 15; ci = ci < 0 ? 0 : (ci > 30 ? 30 : ci);
;                   const float bias = *(const LAS float*)(lds + NA_RPB + ((h * 15 + rowidx0 + a) * 31 + ci) * 4);
;                   S[a][q >> 2][q & 3] = valid ? S[a][q >> 2][q & 3] + bias : -1e30f; } }
	v_add_f32_e32 v213, v105, v213
	v_cndmask_b32_e64 v150, v150, v213, s[30:31]
	v_pk_mul_f32 v[104:105], v[158:159], v[162:163]
	v_pk_mul_f32 v[106:107], v[156:157], v[160:161]
	v_mov_b32_e32 v152, 0xf149f2ca
	v_mov_b32_e32 v153, 0xf149f2ca
	v_add_u32_e32 v210, s17, v242
	v_lshl_add_u32 v210, v210, 2, 0
	v_add_u32_e32 v210, 0x11000, v210
	ds_read_b32 v210, v210
	v_add_u32_e32 v211, s17, v243
	v_lshl_add_u32 v211, v211, 2, 0
	v_add_u32_e32 v211, 0x11000, v211
	ds_read_b32 v211, v211
	v_add_u32_e32 v212, s17, v244
	v_lshl_add_u32 v212, v212, 2, 0
	v_add_u32_e32 v212, 0x11000, v212
	ds_read_b32 v212, v212
	v_add_u32_e32 v213, s17, v245
	v_lshl_add_u32 v213, v213, 2, 0
	v_add_u32_e32 v213, 0x11000, v213
	ds_read_b32 v213, v213
	s_waitcnt lgkmcnt(3)
	v_add_f32_e32 v210, v106, v210
	v_cndmask_b32_e64 v153, v153, v210, s[36:37]
	s_waitcnt lgkmcnt(2)
	v_add_f32_e32 v211, v107, v211
	v_cndmask_b32_e64 v152, v152, v211, s[38:39]
	v_mov_b32_e32 v154, 0xf149f2ca
	v_mov_b32_e32 v155, 0xf149f2ca
	s_waitcnt lgkmcnt(1)
	v_add_f32_e32 v212, v104, v212
	v_cndmask_b32_e64 v155, v155, v212, s[44:45]
	s_waitcnt lgkmcnt(0)
	v_add_f32_e32 v213, v105, v213
	v_cndmask_b32_e64 v154, v154, v213, s[0:1]
	v_pk_mul_f32 v[104:105], v[130:131], v[134:135]
	v_pk_mul_f32 v[106:107], v[128:129], v[132:133]
	s_add_i32 s17, s15, 0x6c
	v_mov_b32_e32 v128, 0xf149f2ca
	v_mov_b32_e32 v129, 0xf149f2ca
	v_add_u32_e32 v210, s17, v238
	v_lshl_add_u32 v210, v210, 2, 0
	v_add_u32_e32 v210, 0x11000, v210
	ds_read_b32 v210, v210
	v_add_u32_e32 v211, s17, v239
	v_lshl_add_u32 v211, v211, 2, 0
	v_add_u32_e32 v211, 0x11000, v211
	ds_read_b32 v211, v211
	v_add_u32_e32 v212, s17, v240
	v_lshl_add_u32 v212, v212, 2, 0
	v_add_u32_e32 v212, 0x11000, v212
	ds_read_b32 v212, v212
	v_add_u32_e32 v213, s17, v241
	v_lshl_add_u32 v213, v213, 2, 0
	v_add_u32_e32 v213, 0x11000, v213
	ds_read_b32 v213, v213
	s_waitcnt lgkmcnt(3)
	v_add_f32_e32 v210, v106, v210
	v_cndmask_b32_e64 v129, v129, v210, s[6:7]
	s_waitcnt lgkmcnt(2)
	v_add_f32_e32 v211, v107, v211
	v_cndmask_b32_e64 v128, v128, v211, s[22:23]
	v_mov_b32_e32 v130, 0xf149f2ca
	v_mov_b32_e32 v131, 0xf149f2ca
	s_waitcnt lgkmcnt(1)
	v_add_f32_e32 v212, v104, v212
	v_cndmask_b32_e64 v131, v131, v212, s[28:29]
	s_waitcnt lgkmcnt(0)
	v_add_f32_e32 v213, v105, v213
	v_cndmask_b32_e64 v130, v130, v213, s[30:31]
	v_pk_mul_f32 v[104:105], v[138:139], v[146:147]
	v_pk_mul_f32 v[106:107], v[136:137], v[144:145]
	v_mov_b32_e32 v132, 0xf149f2ca
	v_mov_b32_e32 v133, 0xf149f2ca
	v_add_u32_e32 v210, s17, v242
	v_lshl_add_u32 v210, v210, 2, 0
	v_add_u32_e32 v210, 0x11000, v210
	ds_read_b32 v210, v210
	v_add_u32_e32 v211, s17, v243
	v_lshl_add_u32 v211, v211, 2, 0
	v_add_u32_e32 v211, 0x11000, v211
	ds_read_b32 v211, v211
	v_add_u32_e32 v212, s17, v244
	v_lshl_add_u32 v212, v212, 2, 0
	v_add_u32_e32 v212, 0x11000, v212
	ds_read_b32 v212, v212
	v_add_u32_e32 v213, s17, v245
	v_lshl_add_u32 v213, v213, 2, 0
	v_add_u32_e32 v213, 0x11000, v213
	ds_read_b32 v213, v213
	s_waitcnt lgkmcnt(3)
	v_add_f32_e32 v210, v106, v210
	v_cndmask_b32_e64 v133, v133, v210, s[36:37]
	s_waitcnt lgkmcnt(2)
	v_add_f32_e32 v211, v107, v211
	v_cndmask_b32_e64 v132, v132, v211, s[38:39]
	v_mov_b32_e32 v134, 0xf149f2ca
	v_mov_b32_e32 v135, 0xf149f2ca
	s_waitcnt lgkmcnt(1)
	v_add_f32_e32 v212, v104, v212
	v_cndmask_b32_e64 v135, v135, v212, s[44:45]
	s_waitcnt lgkmcnt(0)
	v_add_f32_e32 v213, v105, v213
	v_cndmask_b32_e64 v134, v134, v213, s[0:1]
	v_pk_mul_f32 v[106:107], v[116:117], v[120:121]
	v_add_u32_e32 v116, s16, v250
	v_mul_lo_u32 v116, v116, 31
	v_pk_mul_f32 v[104:105], v[118:119], v[122:123]
	v_add_u32_e32 v120, 15, v116
	v_mov_b32_e32 v116, 0xf149f2ca
	v_mov_b32_e32 v117, 0xf149f2ca
	v_add_u32_e32 v210, v120, v238
	v_lshl_add_u32 v210, v210, 2, 0
	v_add_u32_e32 v210, 0x11000, v210
	ds_read_b32 v210, v210
	v_add_u32_e32 v211, v120, v239
	v_lshl_add_u32 v211, v211, 2, 0
	v_add_u32_e32 v211, 0x11000, v211
	ds_read_b32 v211, v211
	v_add_u32_e32 v212, v120, v240
	v_lshl_add_u32 v212, v212, 2, 0
	v_add_u32_e32 v212, 0x11000, v212
	ds_read_b32 v212, v212
	v_add_u32_e32 v213, v120, v241
	v_lshl_add_u32 v213, v213, 2, 0
	v_add_u32_e32 v213, 0x11000, v213
	ds_read_b32 v213, v213
	s_waitcnt lgkmcnt(3)
	v_add_f32_e32 v210, v106, v210
	v_cndmask_b32_e64 v117, v117, v210, s[6:7]
	s_waitcnt lgkmcnt(2)
	v_add_f32_e32 v211, v107, v211
	v_cndmask_b32_e64 v116, v116, v211, s[22:23]
	v_mov_b32_e32 v118, 0xf149f2ca
	v_mov_b32_e32 v119, 0xf149f2ca
	s_waitcnt lgkmcnt(1)
	v_add_f32_e32 v212, v104, v212
	v_cndmask_b32_e64 v119, v119, v212, s[28:29]
	s_waitcnt lgkmcnt(0)
	v_add_f32_e32 v213, v105, v213
	v_cndmask_b32_e64 v118, v118, v213, s[30:31]
	v_pk_mul_f32 v[104:105], v[114:115], v[126:127]
	v_pk_mul_f32 v[106:107], v[112:113], v[124:125]
	v_mov_b32_e32 v112, 0xf149f2ca
	v_mov_b32_e32 v113, 0xf149f2ca
	v_add_u32_e32 v210, v120, v242
	v_lshl_add_u32 v210, v210, 2, 0
	v_add_u32_e32 v210, 0x11000, v210
	ds_read_b32 v210, v210
	v_add_u32_e32 v211, v120, v243
	v_lshl_add_u32 v211, v211, 2, 0
	v_add_u32_e32 v211, 0x11000, v211
	ds_read_b32 v211, v211
	v_add_u32_e32 v212, v120, v244
	v_lshl_add_u32 v212, v212, 2, 0
	v_add_u32_e32 v212, 0x11000, v212
	ds_read_b32 v212, v212
	v_add_u32_e32 v213, v120, v245
	v_lshl_add_u32 v213, v213, 2, 0
	v_add_u32_e32 v213, 0x11000, v213
	ds_read_b32 v213, v213
	s_waitcnt lgkmcnt(3)
	v_add_f32_e32 v210, v106, v210
	v_cndmask_b32_e64 v113, v113, v210, s[36:37]
	s_waitcnt lgkmcnt(2)
	v_add_f32_e32 v211, v107, v211
	v_cndmask_b32_e64 v112, v112, v211, s[38:39]
	v_mov_b32_e32 v106, 0xf149f2ca
	v_mov_b32_e32 v107, 0xf149f2ca
	s_waitcnt lgkmcnt(1)
; #define LAS __attribute__((address_space(3)))
; __device__ __forceinline__ void na_attn_block(LAS unsigned char* lds, rsrc_t R, int l, int bx, int G, int tid, int lane, int wave) {
;     ...
;         { const int rowidx0 = start - r + 7;
; #pragma unroll
;           for (int a = 0; a < 8; ++a)
; #pragma unroll
;               for (int q = 0; q < 8; ++q) { const int kcol = kc0 + 16 * (q >> 2) + 4 * kq + (q & 3); const bool valid = (kcol >= cs) && (kcol < cs + 16);
;                   int ci = kcol - qcol + 15; ci = ci < 0 ? 0 : (ci > 30 ? 30 : ci);
;                   const float bias = *(const LAS float*)(lds + NA_RPB + ((h * 15 + rowidx0 + a) * 31 + ci) * 4);
;                   S[a][q >> 2][q & 3] = valid ? S[a][q >> 2][q & 3] + bias : -1e30f; } }
	v_add_f32_e32 v212, v104, v212
	v_cndmask_b32_e64 v107, v107, v212, s[44:45]
	s_waitcnt lgkmcnt(0)
	v_add_f32_e32 v213, v105, v213
	v_cndmask_b32_e64 v106, v106, v213, s[0:1]
	v_pk_mul_f32 v[94:95], v[94:95], v[98:99]
	v_pk_mul_f32 v[92:93], v[92:93], v[96:97]
	s_add_i32 s16, s15, 0xaa
	v_mov_b32_e32 v96, 0xf149f2ca
	v_mov_b32_e32 v97, 0xf149f2ca
	v_add_u32_e32 v210, s16, v238
	v_lshl_add_u32 v210, v210, 2, 0
	v_add_u32_e32 v210, 0x11000, v210
	ds_read_b32 v210, v210
	v_add_u32_e32 v211, s16, v239
	v_lshl_add_u32 v211, v211, 2, 0
	v_add_u32_e32 v211, 0x11000, v211
	ds_read_b32 v211, v211
	v_add_u32_e32 v212, s16, v240
	v_lshl_add_u32 v212, v212, 2, 0
	v_add_u32_e32 v212, 0x11000, v212
	ds_read_b32 v212, v212
	v_add_u32_e32 v213, s16, v241
	v_lshl_add_u32 v213, v213, 2, 0
	v_add_u32_e32 v213, 0x11000, v213
	ds_read_b32 v213, v213
	s_waitcnt lgkmcnt(3)
	v_add_f32_e32 v210, v92, v210
	v_cndmask_b32_e64 v97, v97, v210, s[6:7]
	s_waitcnt lgkmcnt(2)
	v_add_f32_e32 v211, v93, v211
	v_cndmask_b32_e64 v96, v96, v211, s[22:23]
	v_mov_b32_e32 v98, 0xf149f2ca
	v_mov_b32_e32 v99, 0xf149f2ca
	s_waitcnt lgkmcnt(1)
	v_add_f32_e32 v212, v94, v212
	v_cndmask_b32_e64 v99, v99, v212, s[28:29]
	s_waitcnt lgkmcnt(0)
	v_add_f32_e32 v213, v95, v213
	v_cndmask_b32_e64 v98, v98, v213, s[30:31]
	v_pk_mul_f32 v[92:93], v[102:103], v[110:111]
	v_pk_mul_f32 v[94:95], v[100:101], v[108:109]
	v_mov_b32_e32 v100, 0xf149f2ca
	v_mov_b32_e32 v105, 0xf149f2ca
	v_add_u32_e32 v210, s16, v242
	v_lshl_add_u32 v210, v210, 2, 0
	v_add_u32_e32 v210, 0x11000, v210
	ds_read_b32 v210, v210
	v_add_u32_e32 v211, s16, v243
	v_lshl_add_u32 v211, v211, 2, 0
	v_add_u32_e32 v211, 0x11000, v211
	ds_read_b32 v211, v211
	v_add_u32_e32 v212, s16, v244
	v_lshl_add_u32 v212, v212, 2, 0
	v_add_u32_e32 v212, 0x11000, v212
	ds_read_b32 v212, v212
	v_add_u32_e32 v213, s16, v245
	v_lshl_add_u32 v213, v213, 2, 0
	v_add_u32_e32 v213, 0x11000, v213
	ds_read_b32 v213, v213
	s_waitcnt lgkmcnt(3)
	v_add_f32_e32 v210, v94, v210
	v_cndmask_b32_e64 v105, v105, v210, s[36:37]
	s_waitcnt lgkmcnt(2)
	v_add_f32_e32 v211, v95, v211
	v_cndmask_b32_e64 v100, v100, v211, s[38:39]
	v_mov_b32_e32 v94, 0xf149f2ca
	v_mov_b32_e32 v95, 0xf149f2ca
	s_waitcnt lgkmcnt(1)
	v_add_f32_e32 v212, v92, v212
	v_cndmask_b32_e64 v95, v95, v212, s[44:45]
	s_waitcnt lgkmcnt(0)
	v_add_f32_e32 v213, v93, v213
	v_cndmask_b32_e64 v94, v94, v213, s[0:1]
	v_pk_mul_f32 v[74:75], v[74:75], v[78:79]
	v_pk_mul_f32 v[72:73], v[72:73], v[76:77]
	s_add_i32 s16, s15, 0xc9
	v_mov_b32_e32 v76, 0xf149f2ca
	v_mov_b32_e32 v77, 0xf149f2ca
	v_add_u32_e32 v210, s16, v238
	v_lshl_add_u32 v210, v210, 2, 0
	v_add_u32_e32 v210, 0x11000, v210
	ds_read_b32 v210, v210
	v_add_u32_e32 v211, s16, v239
	v_lshl_add_u32 v211, v211, 2, 0
	v_add_u32_e32 v211, 0x11000, v211
	ds_read_b32 v211, v211
	v_add_u32_e32 v212, s16, v240
	v_lshl_add_u32 v212, v212, 2, 0
	v_add_u32_e32 v212, 0x11000, v212
	ds_read_b32 v212, v212
	v_add_u32_e32 v213, s16, v241
	v_lshl_add_u32 v213, v213, 2, 0
	v_add_u32_e32 v213, 0x11000, v213
	ds_read_b32 v213, v213
	s_waitcnt lgkmcnt(3)
	v_add_f32_e32 v210, v72, v210
	v_cndmask_b32_e64 v77, v77, v210, s[6:7]
	s_waitcnt lgkmcnt(2)
	v_add_f32_e32 v211, v73, v211
	v_cndmask_b32_e64 v76, v76, v211, s[22:23]
	v_mov_b32_e32 v78, 0xf149f2ca
	v_mov_b32_e32 v79, 0xf149f2ca
	s_waitcnt lgkmcnt(1)
	v_add_f32_e32 v212, v74, v212
	v_cndmask_b32_e64 v79, v79, v212, s[28:29]
	s_waitcnt lgkmcnt(0)
	v_add_f32_e32 v213, v75, v213
	v_cndmask_b32_e64 v78, v78, v213, s[30:31]
	v_pk_mul_f32 v[72:73], v[82:83], v[90:91]
	v_pk_mul_f32 v[74:75], v[80:81], v[88:89]
	v_mov_b32_e32 v80, 0xf149f2ca
	v_mov_b32_e32 v81, 0xf149f2ca
	v_add_u32_e32 v210, s16, v242
	v_lshl_add_u32 v210, v210, 2, 0
	v_add_u32_e32 v210, 0x11000, v210
	ds_read_b32 v210, v210
	v_add_u32_e32 v211, s16, v243
	v_lshl_add_u32 v211, v211, 2, 0
	v_add_u32_e32 v211, 0x11000, v211
	ds_read_b32 v211, v211
	v_add_u32_e32 v212, s16, v244
	v_lshl_add_u32 v212, v212, 2, 0
	v_add_u32_e32 v212, 0x11000, v212
	ds_read_b32 v212, v212
	v_add_u32_e32 v213, s16, v245
	v_lshl_add_u32 v213, v213, 2, 0
	v_add_u32_e32 v213, 0x11000, v213
	ds_read_b32 v213, v213
	s_waitcnt lgkmcnt(3)
	v_add_f32_e32 v210, v74, v210
	v_cndmask_b32_e64 v81, v81, v210, s[36:37]
	s_waitcnt lgkmcnt(2)
	v_add_f32_e32 v211, v75, v211
	v_cndmask_b32_e64 v80, v80, v211, s[38:39]
	v_mov_b32_e32 v82, 0xf149f2ca
	v_mov_b32_e32 v83, 0xf149f2ca
	s_waitcnt lgkmcnt(1)
	v_add_f32_e32 v212, v72, v212
	v_cndmask_b32_e64 v83, v83, v212, s[44:45]
	s_waitcnt lgkmcnt(0)
	v_add_f32_e32 v213, v73, v213
	v_cndmask_b32_e64 v82, v82, v213, s[0:1]
	v_pk_mul_f32 v[72:73], v[86:87], v[142:143]
	v_pk_mul_f32 v[74:75], v[84:85], v[140:141]
	s_addk_i32 s15, 0xe8
	v_mov_b32_e32 v84, 0xf149f2ca
	v_mov_b32_e32 v85, 0xf149f2ca
	v_add_u32_e32 v210, s15, v238
	v_lshl_add_u32 v210, v210, 2, 0
	v_add_u32_e32 v210, 0x11000, v210
	ds_read_b32 v210, v210
	v_add_u32_e32 v211, s15, v239
	v_lshl_add_u32 v211, v211, 2, 0
	v_add_u32_e32 v211, 0x11000, v211
	ds_read_b32 v211, v211
	v_add_u32_e32 v212, s15, v240
	v_lshl_add_u32 v212, v212, 2, 0
	v_add_u32_e32 v212, 0x11000, v212
	ds_read_b32 v212, v212
	v_add_u32_e32 v213, s15, v241
	v_lshl_add_u32 v213, v213, 2, 0
	v_add_u32_e32 v213, 0x11000, v213
	ds_read_b32 v213, v213
	s_waitcnt lgkmcnt(3)
	v_add_f32_e32 v210, v74, v210
	v_cndmask_b32_e64 v85, v85, v210, s[6:7]
	s_waitcnt lgkmcnt(2)
	v_add_f32_e32 v211, v75, v211
	v_cndmask_b32_e64 v84, v84, v211, s[22:23]
	v_mov_b32_e32 v74, 0xf149f2ca
	v_mov_b32_e32 v75, 0xf149f2ca
	s_waitcnt lgkmcnt(1)
	v_add_f32_e32 v212, v72, v212
	v_cndmask_b32_e64 v75, v75, v212, s[28:29]
	s_waitcnt lgkmcnt(0)
	v_add_f32_e32 v213, v73, v213
	v_cndmask_b32_e64 v74, v74, v213, s[30:31]
	v_pk_mul_f32 v[66:67], v[70:71], v[66:67]
	v_pk_mul_f32 v[64:65], v[68:69], v[64:65]
	v_mov_b32_e32 v68, 0xf149f2ca
	v_mov_b32_e32 v69, 0xf149f2ca
	v_add_u32_e32 v210, s15, v242
	v_lshl_add_u32 v210, v210, 2, 0
	v_add_u32_e32 v210, 0x11000, v210
	ds_read_b32 v210, v210
	v_add_u32_e32 v211, s15, v243
	v_lshl_add_u32 v211, v211, 2, 0
	v_add_u32_e32 v211, 0x11000, v211
	ds_read_b32 v211, v211
	v_add_u32_e32 v212, s15, v244
	v_lshl_add_u32 v212, v212, 2, 0
	v_add_u32_e32 v212, 0x11000, v212
	ds_read_b32 v212, v212
	v_add_u32_e32 v213, s15, v245
	v_lshl_add_u32 v213, v213, 2, 0
	v_add_u32_e32 v213, 0x11000, v213
	ds_read_b32 v213, v213
	s_waitcnt lgkmcnt(3)
	v_add_f32_e32 v210, v64, v210
	v_cndmask_b32_e64 v69, v69, v210, s[36:37]
	s_waitcnt lgkmcnt(2)
	v_add_f32_e32 v211, v65, v211
	v_cndmask_b32_e64 v68, v68, v211, s[38:39]
	v_mov_b32_e32 v64, 0xf149f2ca
	v_mov_b32_e32 v65, 0xf149f2ca
	s_waitcnt lgkmcnt(1)
	v_add_f32_e32 v212, v66, v212
	v_cndmask_b32_e64 v65, v65, v212, s[44:45]
	s_waitcnt lgkmcnt(0)
	v_add_f32_e32 v213, v67, v213
	v_cndmask_b32_e64 v64, v64, v213, s[0:1]
	s_branch .LBB0_184

; __device__ __forceinline__ float sum_fq(float v) { v += __shfl_xor(v, 16); v += __shfl_xor(v, 32); return v; }
; #define LAS __attribute__((address_space(3)))
; #define SCHED_FENCE() __builtin_amdgcn_sched_barrier(0)
; #define NA_ISSUE(seq_, slot_) do { _Pragma("unroll") for (int j = 0; j < 4; ++j) st[slot_][j] = bld<u32x4>(R, co, ((seq_) < 8 ? (unsigned)WS_KB + rowb + (unsigned)((seq_) * 131072) : OFF_VT + rowb + (unsigned)(((seq_) - 8) * 131072)) + (unsigned)j * 8192u); } while (0)
; __device__ __forceinline__ void na_attn_block(LAS unsigned char* lds, rsrc_t R, int l, int bx, int G, int tid, int lane, int wave) {
;     ...
;         const int hp = u & 3, r = (u >> 2) & 127, b = u >> 9, h = 2 * hp + hsel;
;         int start = r - 4; start = start < 0 ? 0 : (start > 120 ? 120 : start);
;         const unsigned rowb = (unsigned)(((b * 128 + start) * 8 + 2 * hp) * 16384);
;         u32x4 st[3][4];
;     ...
;         u32x4 qraw[4]; float s0, s1;
;         { const unsigned q_off = OFF_PROJ + (unsigned)((b * SEQ + r * 64 + 16 * qg) * PROJ_W + h * HD) * 2u;
; #pragma unroll
;           for (int ks = 0; ks < 4; ++ks) qraw[ks] = bld<u32x4>(R, qo, q_off + 64 * ks);
;           const int hs = wave & 1, a0 = wave >> 1;
;           const unsigned sso = OFF_SS + (unsigned)(SS_H + (size_t)(l * 20 + 2 * hp + hs) * NTOK + b * SEQ + (start + a0) * 64) * 4u;
;           s0 = bld<float>(R, (unsigned)(lane * 4), sso); s1 = bld<float>(R, (unsigned)(lane * 4), sso + 4u * 64u * 4u); }
;         SCHED_FENCE();
;         NA_ISSUE(0, 0); NA_ISSUE(1, 1); NA_ISSUE(2, 2);
;         SCHED_FENCE();
;         *(LAS float*)(lds + NA_SSK + tid * 4) = __builtin_amdgcn_rsqf(s0 * (1.f / HD) + EPS); *(LAS float*)(lds + NA_SSK + (tid + 512) * 4) = __builtin_amdgcn_rsqf(s1 * (1.f / HD) + EPS);
;         bf16x8 qf[4];
;         { float qv[4][8]; float ss = 0.f;
; #pragma unroll
;           for (int ks = 0; ks < 4; ++ks)
; #pragma unroll
;               for (int j = 0; j < 4; ++j) { const unsigned w = qraw[ks][j]; qv[ks][2 * j] = __builtin_bit_cast(float, w << 16); qv[ks][2 * j + 1] = __builtin_bit_cast(float, w & 0xffff0000u); ss += qv[ks][2 * j] * qv[ks][2 * j] + qv[ks][2 * j + 1] * qv[ks][2 * j + 1]; }
;           ss = pg8::sum_fq(ss);
;           const float rq = __builtin_amdgcn_rsqf(ss * (1.f / HD) + EPS);
.Lna2_185:
	s_bfe_u32 s2, s11, 0x70002
	v_med3_u32 v250, s2, 4, v222
	s_ashr_i32 s16, s11, 9
	v_readfirstlane_b32 s15, v250
	s_add_i32 s15, s15, -4
	s_lshl_b32 s12, s16, 10
	s_lshl_b32 s13, s15, 3
	s_and_b32 s17, s10, 6
	s_add_i32 s13, s13, s12
	s_or_b32 s14, s13, s17
	s_lshl_b32 s12, s16, 13
	s_lshl_b32 s13, s2, 6
	v_readlane_b32 s3, v253, 32
	s_or_b32 s12, s13, s12
	v_readlane_b32 s13, v253, 30
	s_add_i32 s3, s17, s3
	s_or_b32 s12, s12, s13
	s_lshl_b32 s13, s3, 8
	s_mul_i32 s18, s12, 0x1800
	s_add_i32 s18, s13, s18
	s_add_i32 s18, s18, 0x14e00000
	s_or_b32 s19, s18, 64
	buffer_load_dwordx4 v[64:67], v232, s[40:43], s18 offen
	buffer_load_dwordx4 v[68:71], v232, s[40:43], s19 offen
	s_or_b32 s19, s18, 0x80
	s_or_b32 s18, s18, 0xc0
	buffer_load_dwordx4 v[84:87], v232, s[40:43], s19 offen
	buffer_load_dwordx4 v[92:95], v232, s[40:43], s18 offen
	s_add_i32 s17, s4, s17
	v_readlane_b32 s18, v253, 37
	s_add_i32 s18, s15, s18
	s_lshl_b32 s17, s17, 17
	s_lshl_b32 s16, s16, 15
	s_lshl_b32 s18, s18, 8
	s_add_i32 s16, s16, s17
	s_add_i32 s16, s16, s18
	s_add_i32 s17, s16, 0x1a0000
	s_add_i32 s16, s16, 0x1a0400
	buffer_load_dword v96, v234, s[40:43], s17 offen
	buffer_load_dword v97, v234, s[40:43], s16 offen
	s_lshl_b32 s14, s14, 14
	s_add_i32 s16, s14, 0x30e00000
	buffer_load_dwordx4 v[72:75], v208, s[40:43], s16 offen
	s_add_i32 s16, s14, 0x30e02000
	buffer_load_dwordx4 v[76:79], v208, s[40:43], s16 offen
	s_add_i32 s16, s14, 0x30e04000
	buffer_load_dwordx4 v[80:83], v208, s[40:43], s16 offen
	s_add_i32 s16, s14, 0x30e06000
	buffer_load_dwordx4 v[88:91], v208, s[40:43], s16 offen
	s_add_i32 s16, s14, 0x30e20000
	buffer_load_dwordx4 v[48:51], v208, s[40:43], s16 offen
	s_add_i32 s16, s14, 0x30e22000
	buffer_load_dwordx4 v[52:55], v208, s[40:43], s16 offen
	s_add_i32 s16, s14, 0x30e24000
	buffer_load_dwordx4 v[56:59], v208, s[40:43], s16 offen
	s_add_i32 s16, s14, 0x30e26000
	buffer_load_dwordx4 v[60:63], v208, s[40:43], s16 offen
	s_add_i32 s16, s14, 0x30e40000
	buffer_load_dwordx4 v[32:35], v208, s[40:43], s16 offen
	s_add_i32 s16, s14, 0x30e42000
	buffer_load_dwordx4 v[36:39], v208, s[40:43], s16 offen
	s_add_i32 s16, s14, 0x30e44000
	buffer_load_dwordx4 v[40:43], v208, s[40:43], s16 offen
	s_add_i32 s16, s14, 0x30e46000
	buffer_load_dwordx4 v[44:47], v208, s[40:43], s16 offen
	s_waitcnt vmcnt(12)
	v_and_b32_e32 v101, 0xffff0000, v64
	v_and_b32_e32 v103, 0xffff0000, v65
	v_lshlrev_b32_e32 v100, 16, v64
	v_mul_f32_e32 v64, v101, v101
	v_lshlrev_b32_e32 v102, 16, v65
	v_mul_f32_e32 v65, v103, v103
	v_fmac_f32_e32 v64, v100, v100
	v_fmac_f32_e32 v65, v102, v102
	v_lshlrev_b32_e32 v104, 16, v66
	v_and_b32_e32 v66, 0xffff0000, v66
	v_add_f32_e32 v64, v64, v65
	v_mul_f32_e32 v65, v66, v66
	v_fmac_f32_e32 v65, v104, v104
	v_lshlrev_b32_e32 v105, 16, v67
	v_and_b32_e32 v67, 0xffff0000, v67
	v_add_f32_e32 v64, v65, v64
	v_mul_f32_e32 v65, v67, v67
	v_fmac_f32_e32 v65, v105, v105
	v_lshlrev_b32_e32 v106, 16, v68
	v_and_b32_e32 v68, 0xffff0000, v68
	v_add_f32_e32 v64, v65, v64
	v_mul_f32_e32 v65, v68, v68
	v_fmac_f32_e32 v65, v106, v106
	v_lshlrev_b32_e32 v107, 16, v69
	v_and_b32_e32 v69, 0xffff0000, v69
	v_add_f32_e32 v64, v65, v64
	v_mul_f32_e32 v65, v69, v69
	v_fmac_f32_e32 v65, v107, v107
	v_lshlrev_b32_e32 v108, 16, v70
	v_and_b32_e32 v70, 0xffff0000, v70
	v_add_f32_e32 v64, v65, v64
	v_mul_f32_e32 v65, v70, v70
	v_fmac_f32_e32 v65, v108, v108
	v_lshlrev_b32_e32 v109, 16, v71
	v_and_b32_e32 v71, 0xffff0000, v71
	v_add_f32_e32 v64, v65, v64
	v_mul_f32_e32 v65, v71, v71
	v_fmac_f32_e32 v65, v109, v109
	v_and_b32_e32 v111, 0xffff0000, v84
	v_add_f32_e32 v64, v65, v64
	v_lshlrev_b32_e32 v110, 16, v84
	v_mul_f32_e32 v65, v111, v111
	v_fmac_f32_e32 v65, v110, v110
	v_and_b32_e32 v113, 0xffff0000, v85
	v_fmamk_f32 v96, v96, 0x3c000000, v218
	v_fmamk_f32 v97, v97, 0x3c000000, v218
	v_add_f32_e32 v64, v65, v64
	v_lshlrev_b32_e32 v112, 16, v85
	v_mul_f32_e32 v65, v113, v113
	v_rsq_f32_e32 v96, v96
	v_rsq_f32_e32 v97, v97
	v_fmac_f32_e32 v65, v112, v112
	v_and_b32_e32 v115, 0xffff0000, v86
	v_add_f32_e32 v64, v65, v64
	v_lshlrev_b32_e32 v114, 16, v86
	v_mul_f32_e32 v65, v115, v115
	v_fmac_f32_e32 v65, v114, v114
	v_and_b32_e32 v117, 0xffff0000, v87
	v_add_f32_e32 v64, v65, v64
	v_lshlrev_b32_e32 v116, 16, v87
	v_mul_f32_e32 v65, v117, v117
	ds_write2st64_b32 v246, v96, v97 offset1:8
	v_fmac_f32_e32 v65, v116, v116
	v_lshlrev_b32_e32 v97, 16, v93
	v_lshlrev_b32_e32 v96, 16, v92
	v_and_b32_e32 v93, 0xffff0000, v93
	v_and_b32_e32 v92, 0xffff0000, v92
	v_add_f32_e32 v84, v65, v64
	v_pk_mul_f32 v[64:65], v[92:93], v[92:93]
	v_lshlrev_b32_e32 v99, 16, v95
	v_pk_fma_f32 v[64:65], v[96:97], v[96:97], v[64:65]
	v_lshlrev_b32_e32 v98, 16, v94
	v_add_f32_e32 v64, v64, v84
	v_and_b32_e32 v95, 0xffff0000, v95
	v_and_b32_e32 v94, 0xffff0000, v94
	v_add_f32_e32 v84, v65, v64
	v_pk_mul_f32 v[64:65], v[94:95], v[94:95]
	v_add_u32_e32 v249, 0, v208
	v_pk_fma_f32 v[64:65], v[98:99], v[98:99], v[64:65]
	s_add_i32 s16, s14, 0x30e60000
	v_add_f32_e32 v64, v64, v84
	v_add_f32_e32 v64, v65, v64
	ds_bpermute_b32 v65, v235, v64
	s_waitcnt lgkmcnt(0)
	v_add_f32_e32 v64, v64, v65
	ds_bpermute_b32 v65, v236, v64
	s_waitcnt lgkmcnt(0)
; __device__ __forceinline__ unsigned cvt_pk_bf16(float lo, float hi) { unsigned r; asm volatile("v_cvt_pk_bf16_f32 %0, %1, %2" : "=v"(r) : "v"(lo), "v"(hi)); return r; }
; #define LAS __attribute__((address_space(3)))
; #define MFMA16(a, b, c) __builtin_amdgcn_mfma_f32_16x16x32_bf16((a), (b), (c), 0, 0, 0)
; #define SCHED_FENCE() __builtin_amdgcn_sched_barrier(0)
; #define NA_ISSUE(seq_, slot_) do { _Pragma("unroll") for (int j = 0; j < 4; ++j) st[slot_][j] = bld<u32x4>(R, co, ((seq_) < 8 ? (unsigned)WS_KB + rowb + (unsigned)((seq_) * 131072) : OFF_VT + rowb + (unsigned)(((seq_) - 8) * 131072)) + (unsigned)j * 8192u); } while (0)
; #define NA_WRITE(slot_, buf_) do { _Pragma("unroll") for (int j = 0; j < 4; ++j) *(LAS u32x4*)(lds + (buf_) * NA_BUF + j * 8192 + tid * 16) = st[slot_][j]; } while (0)
; __device__ __forceinline__ void na_attn_block(LAS unsigned char* lds, rsrc_t R, int l, int bx, int G, int tid, int lane, int wave) {
;     ...
;           for (int ks = 0; ks < 4; ++ks) { const f32x4 g0 = gq[ks][0], g1 = gq[ks][1];
;               u32x4 w; w.x = pg8::cvt_pk_bf16(qv[ks][0] * rq * g0[0], qv[ks][1] * rq * g0[1]); w.y = pg8::cvt_pk_bf16(qv[ks][2] * rq * g0[2], qv[ks][3] * rq * g0[3]);
;               w.z = pg8::cvt_pk_bf16(qv[ks][4] * rq * g1[0], qv[ks][5] * rq * g1[1]); w.w = pg8::cvt_pk_bf16(qv[ks][6] * rq * g1[2], qv[ks][7] * rq * g1[3]);
;               qf[ks] = __builtin_bit_cast(bf16x8, w); } }
;         NA_WRITE(0, 0);
;         __syncthreads();
;         f32x4 S[8][2];
; #pragma unroll
;         for (int a = 0; a < 8; ++a) {
;             NA_ISSUE(a + 3, a % 3);
;             SCHED_FENCE();
;             const int buf = (a & 1) * NA_BUF;
; #pragma unroll
;             for (int t = 0; t < 2; ++t) {
;                 f32x4 acc = (f32x4){0.f, 0.f, 0.f, 0.f};
; #pragma unroll
;                 for (int ks = 0; ks < 4; ++ks) { const bf16x8 kf = *(const LAS bf16x8*)(lds + kfb + buf + t * 4096 + ks * 512); acc = MFMA16(kf, qf[ks], acc); }
;                 const f32x4 rk = *(const LAS f32x4*)(lds + skb + a * 512 + t * 64);
;                 S[a][t] = acc * rk;
;             }
;             SCHED_FENCE();
;             NA_WRITE((a + 1) % 3, (a + 1) & 1);
;             __syncthreads();
;         }
	v_add_f32_e32 v64, v64, v65
	v_fmamk_f32 v64, v64, 0x3c000000, v218
	v_rsq_f32_e32 v118, v64
	s_nop 0
	v_mul_f32_e32 v64, v118, v100
	v_mul_f32_e32 v65, v118, v101
	v_mul_f32_e32 v64, v28, v64
	v_mul_f32_e32 v65, v29, v65
	v_cvt_pk_bf16_f32 v84, v64, v65
	v_mul_f32_e32 v64, v118, v102
	v_mul_f32_e32 v65, v118, v103
	v_mul_f32_e32 v64, v30, v64
	v_mul_f32_e32 v65, v31, v65
	v_cvt_pk_bf16_f32 v85, v64, v65
	v_mul_f32_e32 v64, v118, v104
	v_mul_f32_e32 v65, v118, v66
	v_mul_f32_e32 v64, v24, v64
	v_mul_f32_e32 v65, v25, v65
	v_cvt_pk_bf16_f32 v86, v64, v65
	v_mul_f32_e32 v64, v118, v105
	v_mul_f32_e32 v65, v118, v67
	v_mul_f32_e32 v64, v26, v64
	v_mul_f32_e32 v65, v27, v65
	v_cvt_pk_bf16_f32 v87, v64, v65
	v_mul_f32_e32 v64, v118, v106
	v_mul_f32_e32 v65, v118, v68
	v_mul_f32_e32 v64, v20, v64
	v_mul_f32_e32 v65, v21, v65
	v_cvt_pk_bf16_f32 v64, v64, v65
	v_mul_f32_e32 v65, v118, v107
	v_mul_f32_e32 v66, v118, v69
	v_mul_f32_e32 v65, v22, v65
	v_mul_f32_e32 v66, v23, v66
	v_cvt_pk_bf16_f32 v65, v65, v66
	v_mul_f32_e32 v66, v118, v108
	v_mul_f32_e32 v67, v118, v70
	v_mul_f32_e32 v66, v16, v66
	v_mul_f32_e32 v67, v17, v67
	v_cvt_pk_bf16_f32 v66, v66, v67
	v_mul_f32_e32 v67, v118, v109
	v_mul_f32_e32 v68, v118, v71
	v_mul_f32_e32 v67, v18, v67
	v_mul_f32_e32 v68, v19, v68
	v_cvt_pk_bf16_f32 v67, v67, v68
	v_mul_f32_e32 v68, v118, v110
	v_mul_f32_e32 v69, v118, v111
	v_mul_f32_e32 v68, v12, v68
	v_mul_f32_e32 v69, v13, v69
	v_cvt_pk_bf16_f32 v68, v68, v69
	v_mul_f32_e32 v69, v118, v112
	v_mul_f32_e32 v70, v118, v113
	v_mul_f32_e32 v69, v14, v69
	v_mul_f32_e32 v70, v15, v70
	v_cvt_pk_bf16_f32 v69, v69, v70
	v_mul_f32_e32 v70, v118, v114
	v_mul_f32_e32 v71, v118, v115
	v_mul_f32_e32 v70, v8, v70
	v_mul_f32_e32 v71, v9, v71
	v_cvt_pk_bf16_f32 v70, v70, v71
	v_mul_f32_e32 v71, v118, v116
	v_mul_f32_e32 v92, v118, v92
	v_mul_f32_e32 v71, v10, v71
	v_mul_f32_e32 v100, v118, v117
	v_mul_f32_e32 v96, v118, v96
	v_mul_f32_e32 v92, v5, v92
	v_mul_f32_e32 v100, v11, v100
	v_cvt_pk_bf16_f32 v71, v71, v100
	v_mul_f32_e32 v96, v4, v96
	v_cvt_pk_bf16_f32 v104, v96, v92
	v_mul_f32_e32 v92, v118, v97
	v_mul_f32_e32 v93, v118, v93
	v_mul_f32_e32 v92, v6, v92
	v_mul_f32_e32 v93, v7, v93
	v_cvt_pk_bf16_f32 v105, v92, v93
	v_mul_f32_e32 v92, v118, v98
	v_mul_f32_e32 v93, v118, v94
	v_mul_f32_e32 v92, v0, v92
	v_mul_f32_e32 v93, v1, v93
	v_cvt_pk_bf16_f32 v106, v92, v93
	v_mul_f32_e32 v92, v118, v99
	v_mul_f32_e32 v93, v118, v95
	v_mul_f32_e32 v92, v2, v92
	v_mul_f32_e32 v93, v3, v93
	v_cvt_pk_bf16_f32 v107, v92, v93
	s_waitcnt vmcnt(8)
	ds_write_b128 v249, v[72:75]
	ds_write_b128 v249, v[76:79] offset:8192
	ds_write_b128 v249, v[80:83] offset:16384
	ds_write_b128 v249, v[88:91] offset:24576
	s_waitcnt lgkmcnt(0)
	s_barrier
	s_waitcnt vmcnt(4)
	ds_write_b128 v249, v[48:51] offset:32768
	ds_write_b128 v249, v[52:55] offset:40960
	ds_write_b128 v249, v[56:59] offset:49152
	ds_write_b128 v249, v[60:63] offset:57344
	buffer_load_dwordx4 v[72:75], v208, s[40:43], s16 offen
	s_add_i32 s16, s14, 0x30e62000
	buffer_load_dwordx4 v[76:79], v208, s[40:43], s16 offen
	s_add_i32 s16, s14, 0x30e64000
	buffer_load_dwordx4 v[80:83], v208, s[40:43], s16 offen
	s_add_i32 s16, s14, 0x30e66000
	buffer_load_dwordx4 v[88:91], v208, s[40:43], s16 offen
	s_nop 0
	s_nop 7
	ds_read_b128 v[210:213], v247
	ds_read_b128 v[224:227], v247 offset:512
	ds_read_b128 v[184:187], v248 offset:64
	ds_read_b128 v[228:231], v247 offset:1024
	ds_read_b128 v[96:99], v248
	s_waitcnt lgkmcnt(4)
	v_mfma_f32_16x16x32_bf16 v[92:95], v[210:213], v[84:87], 0
	ds_read_b128 v[210:213], v247 offset:1536
	s_waitcnt lgkmcnt(4)
	v_mfma_f32_16x16x32_bf16 v[92:95], v[224:227], v[64:67], v[92:95]
	ds_read_b128 v[224:227], v247 offset:4096
	s_waitcnt lgkmcnt(3)
	v_mfma_f32_16x16x32_bf16 v[92:95], v[228:231], v[68:71], v[92:95]
	ds_read_b128 v[228:231], v247 offset:4608
	s_waitcnt lgkmcnt(2)
	v_mfma_f32_16x16x32_bf16 v[92:95], v[210:213], v[104:107], v[92:95]
	ds_read_b128 v[210:213], v247 offset:5120
	s_nop 6
	v_pk_mul_f32 v[214:215], v[94:95], v[98:99]
	v_pk_mul_f32 v[216:217], v[92:93], v[96:97]
	s_waitcnt lgkmcnt(2)
	v_mfma_f32_16x16x32_bf16 v[92:95], v[224:227], v[84:87], 0
	ds_read_b128 v[224:227], v247 offset:5632
	s_waitcnt lgkmcnt(2)
	v_mfma_f32_16x16x32_bf16 v[92:95], v[228:231], v[64:67], v[92:95]
	s_waitcnt lgkmcnt(1)
	v_mfma_f32_16x16x32_bf16 v[92:95], v[210:213], v[68:71], v[92:95]
	s_waitcnt lgkmcnt(0)
	v_mfma_f32_16x16x32_bf16 v[176:179], v[224:227], v[104:107], v[92:95]
	s_nop 7
	s_nop 0
	s_add_i32 s16, s14, 0x30e80000
	s_waitcnt lgkmcnt(0)
	s_barrier
	s_waitcnt vmcnt(4)
	ds_write_b128 v249, v[32:35]
	ds_write_b128 v249, v[36:39] offset:8192
	ds_write_b128 v249, v[40:43] offset:16384
	ds_write_b128 v249, v[44:47] offset:24576
	buffer_load_dwordx4 v[48:51], v208, s[40:43], s16 offen
	s_add_i32 s16, s14, 0x30e82000
	buffer_load_dwordx4 v[52:55], v208, s[40:43], s16 offen
	s_add_i32 s16, s14, 0x30e84000
	buffer_load_dwordx4 v[56:59], v208, s[40:43], s16 offen
	s_add_i32 s16, s14, 0x30e86000
	buffer_load_dwordx4 v[92:95], v208, s[40:43], s16 offen
	s_nop 0
	s_nop 7
	ds_read_b128 v[210:213], v247 offset:32768
	ds_read_b128 v[224:227], v247 offset:33280
	ds_read_b128 v[228:231], v247 offset:33792
	ds_read_b128 v[168:171], v248 offset:512
	ds_read_b128 v[180:183], v248 offset:576
	s_waitcnt lgkmcnt(4)
	v_mfma_f32_16x16x32_bf16 v[60:63], v[210:213], v[84:87], 0
	ds_read_b128 v[210:213], v247 offset:34304
	s_waitcnt lgkmcnt(4)
	v_mfma_f32_16x16x32_bf16 v[60:63], v[224:227], v[64:67], v[60:63]
	ds_read_b128 v[224:227], v247 offset:36864
	s_waitcnt lgkmcnt(4)
	v_mfma_f32_16x16x32_bf16 v[60:63], v[228:231], v[68:71], v[60:63]
	ds_read_b128 v[228:231], v247 offset:37376
	s_waitcnt lgkmcnt(2)
	v_mfma_f32_16x16x32_bf16 v[164:167], v[210:213], v[104:107], v[60:63]
	ds_read_b128 v[210:213], v247 offset:37888
	s_waitcnt lgkmcnt(2)
	v_mfma_f32_16x16x32_bf16 v[60:63], v[224:227], v[84:87], 0
	ds_read_b128 v[224:227], v247 offset:38400
	s_waitcnt lgkmcnt(2)
	v_mfma_f32_16x16x32_bf16 v[60:63], v[228:231], v[64:67], v[60:63]
	s_waitcnt lgkmcnt(1)
	v_mfma_f32_16x16x32_bf16 v[60:63], v[210:213], v[68:71], v[60:63]
	s_waitcnt lgkmcnt(0)
	v_mfma_f32_16x16x32_bf16 v[172:175], v[224:227], v[104:107], v[60:63]
	s_nop 7
	s_nop 0
	s_add_i32 s16, s14, 0x30ea0000
	s_waitcnt lgkmcnt(0)
	s_barrier
; #define LAS __attribute__((address_space(3)))
; #define MFMA16(a, b, c) __builtin_amdgcn_mfma_f32_16x16x32_bf16((a), (b), (c), 0, 0, 0)
; #define SCHED_FENCE() __builtin_amdgcn_sched_barrier(0)
; #define NA_ISSUE(seq_, slot_) do { _Pragma("unroll") for (int j = 0; j < 4; ++j) st[slot_][j] = bld<u32x4>(R, co, ((seq_) < 8 ? (unsigned)WS_KB + rowb + (unsigned)((seq_) * 131072) : OFF_VT + rowb + (unsigned)(((seq_) - 8) * 131072)) + (unsigned)j * 8192u); } while (0)
; #define NA_WRITE(slot_, buf_) do { _Pragma("unroll") for (int j = 0; j < 4; ++j) *(LAS u32x4*)(lds + (buf_) * NA_BUF + j * 8192 + tid * 16) = st[slot_][j]; } while (0)
; __device__ __forceinline__ void na_attn_block(LAS unsigned char* lds, rsrc_t R, int l, int bx, int G, int tid, int lane, int wave) {
;     ...
; #pragma unroll
;         for (int a = 0; a < 8; ++a) {
;             NA_ISSUE(a + 3, a % 3);
;             SCHED_FENCE();
;             const int buf = (a & 1) * NA_BUF;
; #pragma unroll
;             for (int t = 0; t < 2; ++t) {
;                 f32x4 acc = (f32x4){0.f, 0.f, 0.f, 0.f};
; #pragma unroll
;                 for (int ks = 0; ks < 4; ++ks) { const bf16x8 kf = *(const LAS bf16x8*)(lds + kfb + buf + t * 4096 + ks * 512); acc = MFMA16(kf, qf[ks], acc); }
;                 const f32x4 rk = *(const LAS f32x4*)(lds + skb + a * 512 + t * 64);
;                 S[a][t] = acc * rk;
;             }
;             SCHED_FENCE();
;             NA_WRITE((a + 1) % 3, (a + 1) & 1);
;             __syncthreads();
;         }
	s_waitcnt vmcnt(7)
	ds_write_b128 v249, v[72:75] offset:32768
	s_waitcnt vmcnt(6)
	ds_write_b128 v249, v[76:79] offset:40960
	s_waitcnt vmcnt(5)
	ds_write_b128 v249, v[80:83] offset:49152
	s_waitcnt vmcnt(4)
	ds_write_b128 v249, v[88:91] offset:57344
	buffer_load_dwordx4 v[32:35], v208, s[40:43], s16 offen
	s_add_i32 s16, s14, 0x30ea2000
	buffer_load_dwordx4 v[40:43], v208, s[40:43], s16 offen
	s_add_i32 s16, s14, 0x30ea4000
	buffer_load_dwordx4 v[60:63], v208, s[40:43], s16 offen
	s_add_i32 s16, s14, 0x30ea6000
	buffer_load_dwordx4 v[96:99], v208, s[40:43], s16 offen
	s_nop 0
	s_nop 7
	ds_read_b128 v[210:213], v247
	ds_read_b128 v[224:227], v247 offset:512
	ds_read_b128 v[228:231], v247 offset:1024
	ds_read_b128 v[152:155], v248 offset:1024
	ds_read_b128 v[160:163], v248 offset:1088
	s_waitcnt lgkmcnt(4)
	v_mfma_f32_16x16x32_bf16 v[36:39], v[210:213], v[84:87], 0
	ds_read_b128 v[210:213], v247 offset:1536
	s_waitcnt lgkmcnt(4)
	v_mfma_f32_16x16x32_bf16 v[36:39], v[224:227], v[64:67], v[36:39]
	ds_read_b128 v[224:227], v247 offset:4096
	s_waitcnt lgkmcnt(4)
	v_mfma_f32_16x16x32_bf16 v[36:39], v[228:231], v[68:71], v[36:39]
	ds_read_b128 v[228:231], v247 offset:4608
	s_waitcnt lgkmcnt(2)
	v_mfma_f32_16x16x32_bf16 v[148:151], v[210:213], v[104:107], v[36:39]
	ds_read_b128 v[210:213], v247 offset:5120
	s_waitcnt lgkmcnt(2)
	v_mfma_f32_16x16x32_bf16 v[36:39], v[224:227], v[84:87], 0
	ds_read_b128 v[224:227], v247 offset:5632
	s_waitcnt lgkmcnt(2)
	v_mfma_f32_16x16x32_bf16 v[36:39], v[228:231], v[64:67], v[36:39]
	s_waitcnt lgkmcnt(1)
	v_mfma_f32_16x16x32_bf16 v[36:39], v[210:213], v[68:71], v[36:39]
	s_waitcnt lgkmcnt(0)
	v_mfma_f32_16x16x32_bf16 v[156:159], v[224:227], v[104:107], v[36:39]
	s_nop 7
	s_nop 0
	s_add_i32 s16, s14, 0x30ec0000
	s_waitcnt lgkmcnt(0)
	s_barrier
	s_waitcnt vmcnt(7)
	ds_write_b128 v249, v[48:51]
	s_waitcnt vmcnt(6)
	ds_write_b128 v249, v[52:55] offset:8192
	s_waitcnt vmcnt(5)
	ds_write_b128 v249, v[56:59] offset:16384
	s_waitcnt vmcnt(4)
	ds_write_b128 v249, v[92:95] offset:24576
	buffer_load_dwordx4 v[36:39], v208, s[40:43], s16 offen
	s_add_i32 s16, s14, 0x30ec2000
	buffer_load_dwordx4 v[44:47], v208, s[40:43], s16 offen
	s_add_i32 s16, s14, 0x30ec4000
	buffer_load_dwordx4 v[72:75], v208, s[40:43], s16 offen
	s_add_i32 s16, s14, 0x30ec6000
	buffer_load_dwordx4 v[76:79], v208, s[40:43], s16 offen
	s_nop 0
	s_nop 7
	ds_read_b128 v[210:213], v247 offset:32768
	ds_read_b128 v[224:227], v247 offset:33280
	ds_read_b128 v[228:231], v247 offset:33792
	ds_read_b128 v[132:135], v248 offset:1536
	ds_read_b128 v[144:147], v248 offset:1600
	s_waitcnt lgkmcnt(4)
	v_mfma_f32_16x16x32_bf16 v[80:83], v[210:213], v[84:87], 0
	ds_read_b128 v[210:213], v247 offset:34304
	s_waitcnt lgkmcnt(4)
	v_mfma_f32_16x16x32_bf16 v[80:83], v[224:227], v[64:67], v[80:83]
	ds_read_b128 v[224:227], v247 offset:36864
	s_waitcnt lgkmcnt(4)
	v_mfma_f32_16x16x32_bf16 v[80:83], v[228:231], v[68:71], v[80:83]
	ds_read_b128 v[228:231], v247 offset:37376
	s_waitcnt lgkmcnt(2)
	v_mfma_f32_16x16x32_bf16 v[128:131], v[210:213], v[104:107], v[80:83]
	ds_read_b128 v[210:213], v247 offset:37888
	s_waitcnt lgkmcnt(2)
	v_mfma_f32_16x16x32_bf16 v[80:83], v[224:227], v[84:87], 0
	ds_read_b128 v[224:227], v247 offset:38400
	s_waitcnt lgkmcnt(2)
	v_mfma_f32_16x16x32_bf16 v[80:83], v[228:231], v[64:67], v[80:83]
	s_waitcnt lgkmcnt(1)
	v_mfma_f32_16x16x32_bf16 v[80:83], v[210:213], v[68:71], v[80:83]
	s_waitcnt lgkmcnt(0)
	v_mfma_f32_16x16x32_bf16 v[136:139], v[224:227], v[104:107], v[80:83]
	s_nop 7
	s_nop 0
	s_add_i32 s16, s14, 0x30ee0000
	s_waitcnt lgkmcnt(0)
	s_barrier
	s_waitcnt vmcnt(7)
	ds_write_b128 v249, v[32:35] offset:32768
	s_waitcnt vmcnt(6)
	ds_write_b128 v249, v[40:43] offset:40960
	s_waitcnt vmcnt(5)
	ds_write_b128 v249, v[60:63] offset:49152
	s_waitcnt vmcnt(4)
	ds_write_b128 v249, v[96:99] offset:57344
	buffer_load_dwordx4 v[48:51], v208, s[40:43], s16 offen
	s_add_i32 s16, s14, 0x30ee2000
	buffer_load_dwordx4 v[52:55], v208, s[40:43], s16 offen
	s_add_i32 s16, s14, 0x30ee4000
	buffer_load_dwordx4 v[140:143], v208, s[40:43], s16 offen
	s_add_i32 s16, s14, 0x30ee6000
	buffer_load_dwordx4 v[192:195], v208, s[40:43], s16 offen
	s_nop 0
	s_nop 7
	ds_read_b128 v[210:213], v247
	ds_read_b128 v[224:227], v247 offset:512
	ds_read_b128 v[228:231], v247 offset:1024
	ds_read_b128 v[120:123], v248 offset:2048
	ds_read_b128 v[124:127], v248 offset:2112
	s_waitcnt lgkmcnt(4)
	v_mfma_f32_16x16x32_bf16 v[56:59], v[210:213], v[84:87], 0
	ds_read_b128 v[210:213], v247 offset:1536
	s_waitcnt lgkmcnt(4)
	v_mfma_f32_16x16x32_bf16 v[56:59], v[224:227], v[64:67], v[56:59]
	ds_read_b128 v[224:227], v247 offset:4096
	s_waitcnt lgkmcnt(4)
	v_mfma_f32_16x16x32_bf16 v[56:59], v[228:231], v[68:71], v[56:59]
	ds_read_b128 v[228:231], v247 offset:4608
	s_waitcnt lgkmcnt(2)
	v_mfma_f32_16x16x32_bf16 v[116:119], v[210:213], v[104:107], v[56:59]
	ds_read_b128 v[210:213], v247 offset:5120
	s_waitcnt lgkmcnt(2)
	v_mfma_f32_16x16x32_bf16 v[56:59], v[224:227], v[84:87], 0
	ds_read_b128 v[224:227], v247 offset:5632
	s_waitcnt lgkmcnt(2)
	v_mfma_f32_16x16x32_bf16 v[56:59], v[228:231], v[64:67], v[56:59]
	s_waitcnt lgkmcnt(1)
	v_mfma_f32_16x16x32_bf16 v[56:59], v[210:213], v[68:71], v[56:59]
	s_waitcnt lgkmcnt(0)
	v_mfma_f32_16x16x32_bf16 v[112:115], v[224:227], v[104:107], v[56:59]
	s_nop 7
	s_nop 0
	s_add_i32 s16, s14, 0x20e00000
	s_waitcnt lgkmcnt(0)
	s_barrier
; #define LAS __attribute__((address_space(3)))
; #define MFMA16(a, b, c) __builtin_amdgcn_mfma_f32_16x16x32_bf16((a), (b), (c), 0, 0, 0)
; #define SCHED_FENCE() __builtin_amdgcn_sched_barrier(0)
; #define NA_ISSUE(seq_, slot_) do { _Pragma("unroll") for (int j = 0; j < 4; ++j) st[slot_][j] = bld<u32x4>(R, co, ((seq_) < 8 ? (unsigned)WS_KB + rowb + (unsigned)((seq_) * 131072) : OFF_VT + rowb + (unsigned)(((seq_) - 8) * 131072)) + (unsigned)j * 8192u); } while (0)
; #define NA_WRITE(slot_, buf_) do { _Pragma("unroll") for (int j = 0; j < 4; ++j) *(LAS u32x4*)(lds + (buf_) * NA_BUF + j * 8192 + tid * 16) = st[slot_][j]; } while (0)
; __device__ __forceinline__ void na_attn_block(LAS unsigned char* lds, rsrc_t R, int l, int bx, int G, int tid, int lane, int wave) {
;     ...
; #pragma unroll
;         for (int a = 0; a < 8; ++a) {
;             NA_ISSUE(a + 3, a % 3);
;             SCHED_FENCE();
;             const int buf = (a & 1) * NA_BUF;
; #pragma unroll
;             for (int t = 0; t < 2; ++t) {
;                 f32x4 acc = (f32x4){0.f, 0.f, 0.f, 0.f};
; #pragma unroll
;                 for (int ks = 0; ks < 4; ++ks) { const bf16x8 kf = *(const LAS bf16x8*)(lds + kfb + buf + t * 4096 + ks * 512); acc = MFMA16(kf, qf[ks], acc); }
;                 const f32x4 rk = *(const LAS f32x4*)(lds + skb + a * 512 + t * 64);
;                 S[a][t] = acc * rk;
;             }
;             SCHED_FENCE();
;             NA_WRITE((a + 1) % 3, (a + 1) & 1);
;             __syncthreads();
;         }
;         { const int rowidx0 = start - r + 7;
; #pragma unroll
;           for (int a = 0; a < 8; ++a)
; #pragma unroll
;               for (int q = 0; q < 8; ++q) { const int kcol = kc0 + 16 * (q >> 2) + 4 * kq + (q & 3); const bool valid = (kcol >= cs) && (kcol < cs + 16);
;                   int ci = kcol - qcol + 15; ci = ci < 0 ? 0 : (ci > 30 ? 30 : ci);
;                   const float bias = *(const LAS float*)(lds + NA_RPB + ((h * 15 + rowidx0 + a) * 31 + ci) * 4);
	s_waitcnt vmcnt(7)
	ds_write_b128 v249, v[36:39]
	s_waitcnt vmcnt(6)
	ds_write_b128 v249, v[44:47] offset:8192
	s_waitcnt vmcnt(5)
	ds_write_b128 v249, v[72:75] offset:16384
	s_waitcnt vmcnt(4)
	ds_write_b128 v249, v[76:79] offset:24576
	buffer_load_dwordx4 v[188:191], v208, s[40:43], s16 offen
	s_add_i32 s16, s14, 0x20e02000
	buffer_load_dwordx4 v[196:199], v208, s[40:43], s16 offen
	s_add_i32 s16, s14, 0x20e04000
	buffer_load_dwordx4 v[200:203], v208, s[40:43], s16 offen
	s_add_i32 s16, s14, 0x20e06000
	buffer_load_dwordx4 v[204:207], v208, s[40:43], s16 offen
	s_nop 0
	s_nop 7
	ds_read_b128 v[210:213], v247 offset:32768
	ds_read_b128 v[224:227], v247 offset:33280
	ds_read_b128 v[228:231], v247 offset:33792
	ds_read_b128 v[96:99], v248 offset:2560
	ds_read_b128 v[108:111], v248 offset:2624
	s_waitcnt lgkmcnt(4)
	v_mfma_f32_16x16x32_bf16 v[32:35], v[210:213], v[84:87], 0
	ds_read_b128 v[210:213], v247 offset:34304
	s_waitcnt lgkmcnt(4)
	v_mfma_f32_16x16x32_bf16 v[32:35], v[224:227], v[64:67], v[32:35]
	ds_read_b128 v[224:227], v247 offset:36864
	s_waitcnt lgkmcnt(4)
	v_mfma_f32_16x16x32_bf16 v[32:35], v[228:231], v[68:71], v[32:35]
	ds_read_b128 v[228:231], v247 offset:37376
	s_waitcnt lgkmcnt(2)
	v_mfma_f32_16x16x32_bf16 v[92:95], v[210:213], v[104:107], v[32:35]
	ds_read_b128 v[210:213], v247 offset:37888
	s_waitcnt lgkmcnt(2)
	v_mfma_f32_16x16x32_bf16 v[32:35], v[224:227], v[84:87], 0
	ds_read_b128 v[224:227], v247 offset:38400
	s_waitcnt lgkmcnt(2)
	v_mfma_f32_16x16x32_bf16 v[32:35], v[228:231], v[64:67], v[32:35]
	s_waitcnt lgkmcnt(1)
	v_mfma_f32_16x16x32_bf16 v[32:35], v[210:213], v[68:71], v[32:35]
	s_waitcnt lgkmcnt(0)
	v_mfma_f32_16x16x32_bf16 v[100:103], v[224:227], v[104:107], v[32:35]
	s_nop 7
	s_nop 0
	s_add_i32 s16, s14, 0x20e20000
	s_waitcnt lgkmcnt(0)
	s_barrier
	s_waitcnt vmcnt(7)
	ds_write_b128 v249, v[48:51] offset:32768
	s_waitcnt vmcnt(6)
	ds_write_b128 v249, v[52:55] offset:40960
	s_waitcnt vmcnt(5)
	ds_write_b128 v249, v[140:143] offset:49152
	s_waitcnt vmcnt(4)
	ds_write_b128 v249, v[192:195] offset:57344
	buffer_load_dwordx4 v[32:35], v208, s[40:43], s16 offen
	s_add_i32 s16, s14, 0x20e22000
	buffer_load_dwordx4 v[40:43], v208, s[40:43], s16 offen
	s_add_i32 s16, s14, 0x20e24000
	buffer_load_dwordx4 v[44:47], v208, s[40:43], s16 offen
	s_add_i32 s16, s14, 0x20e26000
	buffer_load_dwordx4 v[56:59], v208, s[40:43], s16 offen
	s_nop 0
	s_nop 7
	ds_read_b128 v[210:213], v247
	ds_read_b128 v[224:227], v247 offset:512
	ds_read_b128 v[228:231], v247 offset:1024
	ds_read_b128 v[76:79], v248 offset:3072
	ds_read_b128 v[88:91], v248 offset:3136
	s_waitcnt lgkmcnt(4)
	v_mfma_f32_16x16x32_bf16 v[36:39], v[210:213], v[84:87], 0
	ds_read_b128 v[210:213], v247 offset:1536
	s_waitcnt lgkmcnt(4)
	v_mfma_f32_16x16x32_bf16 v[36:39], v[224:227], v[64:67], v[36:39]
	ds_read_b128 v[224:227], v247 offset:4096
	s_waitcnt lgkmcnt(4)
	v_mfma_f32_16x16x32_bf16 v[36:39], v[228:231], v[68:71], v[36:39]
	ds_read_b128 v[228:231], v247 offset:4608
	s_waitcnt lgkmcnt(2)
	v_mfma_f32_16x16x32_bf16 v[72:75], v[210:213], v[104:107], v[36:39]
	ds_read_b128 v[210:213], v247 offset:5120
	s_waitcnt lgkmcnt(2)
	v_mfma_f32_16x16x32_bf16 v[36:39], v[224:227], v[84:87], 0
	ds_read_b128 v[224:227], v247 offset:5632
	s_waitcnt lgkmcnt(2)
	v_mfma_f32_16x16x32_bf16 v[36:39], v[228:231], v[64:67], v[36:39]
	s_waitcnt lgkmcnt(1)
	v_mfma_f32_16x16x32_bf16 v[36:39], v[210:213], v[68:71], v[36:39]
	s_waitcnt lgkmcnt(0)
	v_mfma_f32_16x16x32_bf16 v[80:83], v[224:227], v[104:107], v[36:39]
	s_nop 7
	s_nop 0
	s_add_i32 s16, s14, 0x20e40000
	s_waitcnt lgkmcnt(0)
	s_barrier
	s_waitcnt vmcnt(7)
	ds_write_b128 v249, v[188:191]
	s_waitcnt vmcnt(6)
	ds_write_b128 v249, v[196:199] offset:8192
	s_waitcnt vmcnt(5)
	ds_write_b128 v249, v[200:203] offset:16384
	s_waitcnt vmcnt(4)
	ds_write_b128 v249, v[204:207] offset:24576
	buffer_load_dwordx4 v[36:39], v208, s[40:43], s16 offen
	s_add_i32 s16, s14, 0x20e42000
	buffer_load_dwordx4 v[48:51], v208, s[40:43], s16 offen
	s_add_i32 s16, s14, 0x20e44000
	buffer_load_dwordx4 v[52:55], v208, s[40:43], s16 offen
	s_add_i32 s16, s14, 0x20e46000
	buffer_load_dwordx4 v[60:63], v208, s[40:43], s16 offen
	s_nop 0
	s_nop 7
	ds_read_b128 v[210:213], v247 offset:32768
	ds_read_b128 v[224:227], v247 offset:36864
	ds_read_b128 v[228:231], v247 offset:33280
	s_waitcnt lgkmcnt(2)
	v_mfma_f32_16x16x32_bf16 v[140:143], v[210:213], v[84:87], 0
	ds_read_b128 v[210:213], v247 offset:33792
	s_waitcnt lgkmcnt(2)
	v_mfma_f32_16x16x32_bf16 v[192:195], v[224:227], v[84:87], 0
	ds_read_b128 v[224:227], v247 offset:34304
	s_waitcnt lgkmcnt(2)
	v_mfma_f32_16x16x32_bf16 v[84:87], v[228:231], v[64:67], v[140:143]
	ds_read_b128 v[228:231], v247 offset:37376
	s_nop 0
	ds_read_b128 v[140:143], v248 offset:3584
	s_waitcnt lgkmcnt(3)
	v_mfma_f32_16x16x32_bf16 v[84:87], v[210:213], v[68:71], v[84:87]
	ds_read_b128 v[210:213], v247 offset:37888
	s_waitcnt lgkmcnt(3)
	v_mfma_f32_16x16x32_bf16 v[84:87], v[224:227], v[104:107], v[84:87]
	ds_read_b128 v[224:227], v247 offset:38400
	s_waitcnt lgkmcnt(3)
	v_mfma_f32_16x16x32_bf16 v[64:67], v[228:231], v[64:67], v[192:195]
	s_waitcnt lgkmcnt(1)
	v_mfma_f32_16x16x32_bf16 v[68:71], v[210:213], v[68:71], v[64:67]
	s_nop 5
	ds_read_b128 v[64:67], v248 offset:3648
	s_waitcnt lgkmcnt(1)
	v_mfma_f32_16x16x32_bf16 v[68:71], v[224:227], v[104:107], v[68:71]
	s_waitcnt lgkmcnt(0)
	s_nop 6
	s_nop 0
	s_mul_i32 s3, s3, 15
	s_sub_i32 s16, s3, s2
	s_add_i32 s16, s16, 7
	s_add_i32 s15, s16, s15
	s_mul_i32 s15, s15, 31
	s_add_i32 s17, s15, 15
	v_mov_b32_e32 v188, 0xf149f2ca
	v_mov_b32_e32 v189, 0xf149f2ca
	s_waitcnt lgkmcnt(0)
	s_barrier
; #define LAS __attribute__((address_space(3)))
; __device__ __forceinline__ void na_attn_block(LAS unsigned char* lds, rsrc_t R, int l, int bx, int G, int tid, int lane, int wave) {
;     ...
;         { const int rowidx0 = start - r + 7;
; #pragma unroll
;           for (int a = 0; a < 8; ++a)
; #pragma unroll
;               for (int q = 0; q < 8; ++q) { const int kcol = kc0 + 16 * (q >> 2) + 4 * kq + (q & 3); const bool valid = (kcol >= cs) && (kcol < cs + 16);
;                   int ci = kcol - qcol + 15; ci = ci < 0 ? 0 : (ci > 30 ? 30 : ci);
;                   const float bias = *(const LAS float*)(lds + NA_RPB + ((h * 15 + rowidx0 + a) * 31 + ci) * 4);
;                   S[a][q >> 2][q & 3] = valid ? S[a][q >> 2][q & 3] + bias : -1e30f; } }
	v_add_u32_e32 v210, s17, v238
	v_lshl_add_u32 v210, v210, 2, 0
	v_add_u32_e32 v210, 0x11000, v210
	ds_read_b32 v210, v210
	v_add_u32_e32 v211, s17, v239
	v_lshl_add_u32 v211, v211, 2, 0
	v_add_u32_e32 v211, 0x11000, v211
	ds_read_b32 v211, v211
	v_add_u32_e32 v212, s17, v240
	v_lshl_add_u32 v212, v212, 2, 0
	v_add_u32_e32 v212, 0x11000, v212
	ds_read_b32 v212, v212
	v_add_u32_e32 v213, s17, v241
	v_lshl_add_u32 v213, v213, 2, 0
	v_add_u32_e32 v213, 0x11000, v213
	ds_read_b32 v213, v213
	v_add_u32_e32 v224, s17, v242
	v_lshl_add_u32 v224, v224, 2, 0
	v_add_u32_e32 v224, 0x11000, v224
	ds_read_b32 v224, v224
	v_add_u32_e32 v225, s17, v243
	v_lshl_add_u32 v225, v225, 2, 0
	v_add_u32_e32 v225, 0x11000, v225
	ds_read_b32 v225, v225
	v_add_u32_e32 v226, s17, v244
	v_lshl_add_u32 v226, v226, 2, 0
	v_add_u32_e32 v226, 0x11000, v226
	ds_read_b32 v226, v226
	v_add_u32_e32 v227, s17, v245
	v_lshl_add_u32 v227, v227, 2, 0
	v_add_u32_e32 v227, 0x11000, v227
	ds_read_b32 v227, v227
	s_waitcnt lgkmcnt(7)
	v_add_f32_e32 v210, v216, v210
	v_cndmask_b32_e64 v189, v189, v210, s[6:7]
	s_waitcnt lgkmcnt(6)
	v_add_f32_e32 v211, v217, v211
	v_cndmask_b32_e64 v188, v188, v211, s[22:23]
	v_mov_b32_e32 v190, 0xf149f2ca
	v_mov_b32_e32 v191, 0xf149f2ca
	s_waitcnt lgkmcnt(5)
	v_add_f32_e32 v212, v214, v212
	v_cndmask_b32_e64 v191, v191, v212, s[28:29]
	s_waitcnt lgkmcnt(4)
	v_add_f32_e32 v213, v215, v213
	v_cndmask_b32_e64 v190, v190, v213, s[30:31]
	v_pk_mul_f32 v[104:105], v[178:179], v[186:187]
	v_pk_mul_f32 v[106:107], v[176:177], v[184:185]
	v_mov_b32_e32 v176, 0xf149f2ca
	v_mov_b32_e32 v177, 0xf149f2ca
	s_waitcnt lgkmcnt(3)
	v_add_f32_e32 v224, v106, v224
	v_cndmask_b32_e64 v177, v177, v224, s[36:37]
	s_waitcnt lgkmcnt(2)
	v_add_f32_e32 v225, v107, v225
	v_cndmask_b32_e64 v176, v176, v225, s[38:39]
	v_mov_b32_e32 v178, 0xf149f2ca
	v_mov_b32_e32 v179, 0xf149f2ca
	s_waitcnt lgkmcnt(1)
	v_add_f32_e32 v226, v104, v226
	v_cndmask_b32_e64 v179, v179, v226, s[44:45]
	s_waitcnt lgkmcnt(0)
	v_add_f32_e32 v227, v105, v227
	v_cndmask_b32_e64 v178, v178, v227, s[0:1]
	v_pk_mul_f32 v[104:105], v[166:167], v[170:171]
	v_pk_mul_f32 v[106:107], v[164:165], v[168:169]
	s_add_i32 s17, s15, 46
	v_mov_b32_e32 v164, 0xf149f2ca
	v_mov_b32_e32 v165, 0xf149f2ca
	v_add_u32_e32 v210, s17, v238
	v_lshl_add_u32 v210, v210, 2, 0
	v_add_u32_e32 v210, 0x11000, v210
	ds_read_b32 v210, v210
	v_add_u32_e32 v211, s17, v239
	v_lshl_add_u32 v211, v211, 2, 0
	v_add_u32_e32 v211, 0x11000, v211
	ds_read_b32 v211, v211
	v_add_u32_e32 v212, s17, v240
	v_lshl_add_u32 v212, v212, 2, 0
	v_add_u32_e32 v212, 0x11000, v212
	ds_read_b32 v212, v212
	v_add_u32_e32 v213, s17, v241
	v_lshl_add_u32 v213, v213, 2, 0
	v_add_u32_e32 v213, 0x11000, v213
	ds_read_b32 v213, v213
	v_add_u32_e32 v224, s17, v242
	v_lshl_add_u32 v224, v224, 2, 0
	v_add_u32_e32 v224, 0x11000, v224
	ds_read_b32 v224, v224
	v_add_u32_e32 v225, s17, v243
	v_lshl_add_u32 v225, v225, 2, 0
	v_add_u32_e32 v225, 0x11000, v225
	ds_read_b32 v225, v225
	v_add_u32_e32 v226, s17, v244
	v_lshl_add_u32 v226, v226, 2, 0
	v_add_u32_e32 v226, 0x11000, v226
	ds_read_b32 v226, v226
	v_add_u32_e32 v227, s17, v245
	v_lshl_add_u32 v227, v227, 2, 0
	v_add_u32_e32 v227, 0x11000, v227
	ds_read_b32 v227, v227
	s_waitcnt lgkmcnt(7)
	v_add_f32_e32 v210, v106, v210
	v_cndmask_b32_e64 v165, v165, v210, s[6:7]
	s_waitcnt lgkmcnt(6)
	v_add_f32_e32 v211, v107, v211
	v_cndmask_b32_e64 v164, v164, v211, s[22:23]
	v_mov_b32_e32 v166, 0xf149f2ca
	v_mov_b32_e32 v167, 0xf149f2ca
	s_waitcnt lgkmcnt(5)
	v_add_f32_e32 v212, v104, v212
	v_cndmask_b32_e64 v167, v167, v212, s[28:29]
	s_waitcnt lgkmcnt(4)
	v_add_f32_e32 v213, v105, v213
	v_cndmask_b32_e64 v166, v166, v213, s[30:31]
	v_pk_mul_f32 v[104:105], v[174:175], v[182:183]
	v_pk_mul_f32 v[106:107], v[172:173], v[180:181]
	v_mov_b32_e32 v168, 0xf149f2ca
	v_mov_b32_e32 v169, 0xf149f2ca
	s_waitcnt lgkmcnt(3)
	v_add_f32_e32 v224, v106, v224
	v_cndmask_b32_e64 v169, v169, v224, s[36:37]
	s_waitcnt lgkmcnt(2)
	v_add_f32_e32 v225, v107, v225
	v_cndmask_b32_e64 v168, v168, v225, s[38:39]
	v_mov_b32_e32 v170, 0xf149f2ca
	v_mov_b32_e32 v171, 0xf149f2ca
	s_waitcnt lgkmcnt(1)
	v_add_f32_e32 v226, v104, v226
	v_cndmask_b32_e64 v171, v171, v226, s[44:45]
	s_waitcnt lgkmcnt(0)
	v_add_f32_e32 v227, v105, v227
	v_cndmask_b32_e64 v170, v170, v227, s[0:1]
	v_pk_mul_f32 v[104:105], v[150:151], v[154:155]
	v_pk_mul_f32 v[106:107], v[148:149], v[152:153]
	s_add_i32 s17, s15, 0x4d
	v_mov_b32_e32 v148, 0xf149f2ca
	v_mov_b32_e32 v149, 0xf149f2ca
	v_add_u32_e32 v210, s17, v238
	v_lshl_add_u32 v210, v210, 2, 0
	v_add_u32_e32 v210, 0x11000, v210
	ds_read_b32 v210, v210
	v_add_u32_e32 v211, s17, v239
	v_lshl_add_u32 v211, v211, 2, 0
	v_add_u32_e32 v211, 0x11000, v211
	ds_read_b32 v211, v211
	v_add_u32_e32 v212, s17, v240
	v_lshl_add_u32 v212, v212, 2, 0
	v_add_u32_e32 v212, 0x11000, v212
	ds_read_b32 v212, v212
	v_add_u32_e32 v213, s17, v241
	v_lshl_add_u32 v213, v213, 2, 0
	v_add_u32_e32 v213, 0x11000, v213
	ds_read_b32 v213, v213
	v_add_u32_e32 v224, s17, v242
	v_lshl_add_u32 v224, v224, 2, 0
	v_add_u32_e32 v224, 0x11000, v224
	ds_read_b32 v224, v224
	v_add_u32_e32 v225, s17, v243
	v_lshl_add_u32 v225, v225, 2, 0
	v_add_u32_e32 v225, 0x11000, v225
	ds_read_b32 v225, v225
	v_add_u32_e32 v226, s17, v244
	v_lshl_add_u32 v226, v226, 2, 0
	v_add_u32_e32 v226, 0x11000, v226
	ds_read_b32 v226, v226
	v_add_u32_e32 v227, s17, v245
	v_lshl_add_u32 v227, v227, 2, 0
	v_add_u32_e32 v227, 0x11000, v227
	ds_read_b32 v227, v227
	s_waitcnt lgkmcnt(7)
	v_add_f32_e32 v210, v106, v210
	v_cndmask_b32_e64 v149, v149, v210, s[6:7]
	s_waitcnt lgkmcnt(6)
; #define LAS __attribute__((address_space(3)))
; __device__ __forceinline__ void na_attn_block(LAS unsigned char* lds, rsrc_t R, int l, int bx, int G, int tid, int lane, int wave) {
;     ...
;         { const int rowidx0 = start - r + 7;
; #pragma unroll
;           for (int a = 0; a < 8; ++a)
; #pragma unroll
;               for (int q = 0; q < 8; ++q) { const int kcol = kc0 + 16 * (q >> 2) + 4 * kq + (q & 3); const bool valid = (kcol >= cs) && (kcol < cs + 16);
;                   int ci = kcol - qcol + 15; ci = ci < 0 ? 0 : (ci > 30 ? 30 : ci);
;                   const float bias = *(const LAS float*)(lds + NA_RPB + ((h * 15 + rowidx0 + a) * 31 + ci) * 4);
;                   S[a][q >> 2][q & 3] = valid ? S[a][q >> 2][q & 3] + bias : -1e30f; } }
	v_add_f32_e32 v211, v107, v211
	v_cndmask_b32_e64 v148, v148, v211, s[22:23]
	v_mov_b32_e32 v150, 0xf149f2ca
	v_mov_b32_e32 v151, 0xf149f2ca
	s_waitcnt lgkmcnt(5)
	v_add_f32_e32 v212, v104, v212
	v_cndmask_b32_e64 v151, v151, v212, s[28:29]
	s_waitcnt lgkmcnt(4)
	v_add_f32_e32 v213, v105, v213
	v_cndmask_b32_e64 v150, v150, v213, s[30:31]
	v_pk_mul_f32 v[104:105], v[158:159], v[162:163]
	v_pk_mul_f32 v[106:107], v[156:157], v[160:161]
	v_mov_b32_e32 v152, 0xf149f2ca
	v_mov_b32_e32 v153, 0xf149f2ca
	s_waitcnt lgkmcnt(3)
	v_add_f32_e32 v224, v106, v224
	v_cndmask_b32_e64 v153, v153, v224, s[36:37]
	s_waitcnt lgkmcnt(2)
	v_add_f32_e32 v225, v107, v225
	v_cndmask_b32_e64 v152, v152, v225, s[38:39]
	v_mov_b32_e32 v154, 0xf149f2ca
	v_mov_b32_e32 v155, 0xf149f2ca
	s_waitcnt lgkmcnt(1)
	v_add_f32_e32 v226, v104, v226
	v_cndmask_b32_e64 v155, v155, v226, s[44:45]
	s_waitcnt lgkmcnt(0)
	v_add_f32_e32 v227, v105, v227
	v_cndmask_b32_e64 v154, v154, v227, s[0:1]
	v_pk_mul_f32 v[104:105], v[130:131], v[134:135]
	v_pk_mul_f32 v[106:107], v[128:129], v[132:133]
	s_add_i32 s17, s15, 0x6c
	v_mov_b32_e32 v128, 0xf149f2ca
	v_mov_b32_e32 v129, 0xf149f2ca
	v_add_u32_e32 v210, s17, v238
	v_lshl_add_u32 v210, v210, 2, 0
	v_add_u32_e32 v210, 0x11000, v210
	ds_read_b32 v210, v210
	v_add_u32_e32 v211, s17, v239
	v_lshl_add_u32 v211, v211, 2, 0
	v_add_u32_e32 v211, 0x11000, v211
	ds_read_b32 v211, v211
	v_add_u32_e32 v212, s17, v240
	v_lshl_add_u32 v212, v212, 2, 0
	v_add_u32_e32 v212, 0x11000, v212
	ds_read_b32 v212, v212
	v_add_u32_e32 v213, s17, v241
	v_lshl_add_u32 v213, v213, 2, 0
	v_add_u32_e32 v213, 0x11000, v213
	ds_read_b32 v213, v213
	v_add_u32_e32 v224, s17, v242
	v_lshl_add_u32 v224, v224, 2, 0
	v_add_u32_e32 v224, 0x11000, v224
	ds_read_b32 v224, v224
	v_add_u32_e32 v225, s17, v243
	v_lshl_add_u32 v225, v225, 2, 0
	v_add_u32_e32 v225, 0x11000, v225
	ds_read_b32 v225, v225
	v_add_u32_e32 v226, s17, v244
	v_lshl_add_u32 v226, v226, 2, 0
	v_add_u32_e32 v226, 0x11000, v226
	ds_read_b32 v226, v226
	v_add_u32_e32 v227, s17, v245
	v_lshl_add_u32 v227, v227, 2, 0
	v_add_u32_e32 v227, 0x11000, v227
	ds_read_b32 v227, v227
	s_waitcnt lgkmcnt(7)
	v_add_f32_e32 v210, v106, v210
	v_cndmask_b32_e64 v129, v129, v210, s[6:7]
	s_waitcnt lgkmcnt(6)
	v_add_f32_e32 v211, v107, v211
	v_cndmask_b32_e64 v128, v128, v211, s[22:23]
	v_mov_b32_e32 v130, 0xf149f2ca
	v_mov_b32_e32 v131, 0xf149f2ca
	s_waitcnt lgkmcnt(5)
	v_add_f32_e32 v212, v104, v212
	v_cndmask_b32_e64 v131, v131, v212, s[28:29]
	s_waitcnt lgkmcnt(4)
	v_add_f32_e32 v213, v105, v213
	v_cndmask_b32_e64 v130, v130, v213, s[30:31]
	v_pk_mul_f32 v[104:105], v[138:139], v[146:147]
	v_pk_mul_f32 v[106:107], v[136:137], v[144:145]
	v_mov_b32_e32 v132, 0xf149f2ca
	v_mov_b32_e32 v133, 0xf149f2ca
	s_waitcnt lgkmcnt(3)
	v_add_f32_e32 v224, v106, v224
	v_cndmask_b32_e64 v133, v133, v224, s[36:37]
	s_waitcnt lgkmcnt(2)
	v_add_f32_e32 v225, v107, v225
	v_cndmask_b32_e64 v132, v132, v225, s[38:39]
	v_mov_b32_e32 v134, 0xf149f2ca
	v_mov_b32_e32 v135, 0xf149f2ca
	s_waitcnt lgkmcnt(1)
	v_add_f32_e32 v226, v104, v226
	v_cndmask_b32_e64 v135, v135, v226, s[44:45]
	s_waitcnt lgkmcnt(0)
	v_add_f32_e32 v227, v105, v227
	v_cndmask_b32_e64 v134, v134, v227, s[0:1]
	v_pk_mul_f32 v[106:107], v[116:117], v[120:121]
	v_add_u32_e32 v116, s16, v250
	v_mul_lo_u32 v116, v116, 31
	v_pk_mul_f32 v[104:105], v[118:119], v[122:123]
	v_add_u32_e32 v120, 15, v116
	v_mov_b32_e32 v116, 0xf149f2ca
	v_mov_b32_e32 v117, 0xf149f2ca
	v_add_u32_e32 v210, v120, v238
	v_lshl_add_u32 v210, v210, 2, 0
	v_add_u32_e32 v210, 0x11000, v210
	ds_read_b32 v210, v210
	v_add_u32_e32 v211, v120, v239
	v_lshl_add_u32 v211, v211, 2, 0
	v_add_u32_e32 v211, 0x11000, v211
	ds_read_b32 v211, v211
	v_add_u32_e32 v212, v120, v240
	v_lshl_add_u32 v212, v212, 2, 0
	v_add_u32_e32 v212, 0x11000, v212
	ds_read_b32 v212, v212
	v_add_u32_e32 v213, v120, v241
	v_lshl_add_u32 v213, v213, 2, 0
	v_add_u32_e32 v213, 0x11000, v213
	ds_read_b32 v213, v213
	v_add_u32_e32 v224, v120, v242
	v_lshl_add_u32 v224, v224, 2, 0
	v_add_u32_e32 v224, 0x11000, v224
	ds_read_b32 v224, v224
	v_add_u32_e32 v225, v120, v243
	v_lshl_add_u32 v225, v225, 2, 0
	v_add_u32_e32 v225, 0x11000, v225
	ds_read_b32 v225, v225
	v_add_u32_e32 v226, v120, v244
	v_lshl_add_u32 v226, v226, 2, 0
	v_add_u32_e32 v226, 0x11000, v226
	ds_read_b32 v226, v226
	v_add_u32_e32 v227, v120, v245
	v_lshl_add_u32 v227, v227, 2, 0
	v_add_u32_e32 v227, 0x11000, v227
	ds_read_b32 v227, v227
	s_waitcnt lgkmcnt(7)
	v_add_f32_e32 v210, v106, v210
	v_cndmask_b32_e64 v117, v117, v210, s[6:7]
	s_waitcnt lgkmcnt(6)
	v_add_f32_e32 v211, v107, v211
	v_cndmask_b32_e64 v116, v116, v211, s[22:23]
	v_mov_b32_e32 v118, 0xf149f2ca
	v_mov_b32_e32 v119, 0xf149f2ca
	s_waitcnt lgkmcnt(5)
	v_add_f32_e32 v212, v104, v212
	v_cndmask_b32_e64 v119, v119, v212, s[28:29]
	s_waitcnt lgkmcnt(4)
	v_add_f32_e32 v213, v105, v213
	v_cndmask_b32_e64 v118, v118, v213, s[30:31]
	v_pk_mul_f32 v[104:105], v[114:115], v[126:127]
	v_pk_mul_f32 v[106:107], v[112:113], v[124:125]
	v_mov_b32_e32 v112, 0xf149f2ca
	v_mov_b32_e32 v113, 0xf149f2ca
	s_waitcnt lgkmcnt(3)
	v_add_f32_e32 v224, v106, v224
	v_cndmask_b32_e64 v113, v113, v224, s[36:37]
	s_waitcnt lgkmcnt(2)
	v_add_f32_e32 v225, v107, v225
	v_cndmask_b32_e64 v112, v112, v225, s[38:39]
	v_mov_b32_e32 v106, 0xf149f2ca
	v_mov_b32_e32 v107, 0xf149f2ca
	s_waitcnt lgkmcnt(1)
	v_add_f32_e32 v226, v104, v226
	v_cndmask_b32_e64 v107, v107, v226, s[44:45]
	s_waitcnt lgkmcnt(0)
; #define LAS __attribute__((address_space(3)))
; __device__ __forceinline__ void na_attn_block(LAS unsigned char* lds, rsrc_t R, int l, int bx, int G, int tid, int lane, int wave) {
;     ...
;         { const int rowidx0 = start - r + 7;
; #pragma unroll
;           for (int a = 0; a < 8; ++a)
; #pragma unroll
;               for (int q = 0; q < 8; ++q) { const int kcol = kc0 + 16 * (q >> 2) + 4 * kq + (q & 3); const bool valid = (kcol >= cs) && (kcol < cs + 16);
;                   int ci = kcol - qcol + 15; ci = ci < 0 ? 0 : (ci > 30 ? 30 : ci);
;                   const float bias = *(const LAS float*)(lds + NA_RPB + ((h * 15 + rowidx0 + a) * 31 + ci) * 4);
;                   S[a][q >> 2][q & 3] = valid ? S[a][q >> 2][q & 3] + bias : -1e30f; } }
	v_add_f32_e32 v227, v105, v227
	v_cndmask_b32_e64 v106, v106, v227, s[0:1]
	v_pk_mul_f32 v[94:95], v[94:95], v[98:99]
	v_pk_mul_f32 v[92:93], v[92:93], v[96:97]
	s_add_i32 s16, s15, 0xaa
	v_mov_b32_e32 v96, 0xf149f2ca
	v_mov_b32_e32 v97, 0xf149f2ca
	v_add_u32_e32 v210, s16, v238
	v_lshl_add_u32 v210, v210, 2, 0
	v_add_u32_e32 v210, 0x11000, v210
	ds_read_b32 v210, v210
	v_add_u32_e32 v211, s16, v239
	v_lshl_add_u32 v211, v211, 2, 0
	v_add_u32_e32 v211, 0x11000, v211
	ds_read_b32 v211, v211
	v_add_u32_e32 v212, s16, v240
	v_lshl_add_u32 v212, v212, 2, 0
	v_add_u32_e32 v212, 0x11000, v212
	ds_read_b32 v212, v212
	v_add_u32_e32 v213, s16, v241
	v_lshl_add_u32 v213, v213, 2, 0
	v_add_u32_e32 v213, 0x11000, v213
	ds_read_b32 v213, v213
	v_add_u32_e32 v224, s16, v242
	v_lshl_add_u32 v224, v224, 2, 0
	v_add_u32_e32 v224, 0x11000, v224
	ds_read_b32 v224, v224
	v_add_u32_e32 v225, s16, v243
	v_lshl_add_u32 v225, v225, 2, 0
	v_add_u32_e32 v225, 0x11000, v225
	ds_read_b32 v225, v225
	v_add_u32_e32 v226, s16, v244
	v_lshl_add_u32 v226, v226, 2, 0
	v_add_u32_e32 v226, 0x11000, v226
	ds_read_b32 v226, v226
	v_add_u32_e32 v227, s16, v245
	v_lshl_add_u32 v227, v227, 2, 0
	v_add_u32_e32 v227, 0x11000, v227
	ds_read_b32 v227, v227
	s_waitcnt lgkmcnt(7)
	v_add_f32_e32 v210, v92, v210
	v_cndmask_b32_e64 v97, v97, v210, s[6:7]
	s_waitcnt lgkmcnt(6)
	v_add_f32_e32 v211, v93, v211
	v_cndmask_b32_e64 v96, v96, v211, s[22:23]
	v_mov_b32_e32 v98, 0xf149f2ca
	v_mov_b32_e32 v99, 0xf149f2ca
	s_waitcnt lgkmcnt(5)
	v_add_f32_e32 v212, v94, v212
	v_cndmask_b32_e64 v99, v99, v212, s[28:29]
	s_waitcnt lgkmcnt(4)
	v_add_f32_e32 v213, v95, v213
	v_cndmask_b32_e64 v98, v98, v213, s[30:31]
	v_pk_mul_f32 v[92:93], v[102:103], v[110:111]
	v_pk_mul_f32 v[94:95], v[100:101], v[108:109]
	v_mov_b32_e32 v100, 0xf149f2ca
	v_mov_b32_e32 v105, 0xf149f2ca
	s_waitcnt lgkmcnt(3)
	v_add_f32_e32 v224, v94, v224
	v_cndmask_b32_e64 v105, v105, v224, s[36:37]
	s_waitcnt lgkmcnt(2)
	v_add_f32_e32 v225, v95, v225
	v_cndmask_b32_e64 v100, v100, v225, s[38:39]
	v_mov_b32_e32 v94, 0xf149f2ca
	v_mov_b32_e32 v95, 0xf149f2ca
	s_waitcnt lgkmcnt(1)
	v_add_f32_e32 v226, v92, v226
	v_cndmask_b32_e64 v95, v95, v226, s[44:45]
	s_waitcnt lgkmcnt(0)
	v_add_f32_e32 v227, v93, v227
	v_cndmask_b32_e64 v94, v94, v227, s[0:1]
	v_pk_mul_f32 v[74:75], v[74:75], v[78:79]
	v_pk_mul_f32 v[72:73], v[72:73], v[76:77]
	s_add_i32 s16, s15, 0xc9
	v_mov_b32_e32 v76, 0xf149f2ca
	v_mov_b32_e32 v77, 0xf149f2ca
	v_add_u32_e32 v210, s16, v238
	v_lshl_add_u32 v210, v210, 2, 0
	v_add_u32_e32 v210, 0x11000, v210
	ds_read_b32 v210, v210
	v_add_u32_e32 v211, s16, v239
	v_lshl_add_u32 v211, v211, 2, 0
	v_add_u32_e32 v211, 0x11000, v211
	ds_read_b32 v211, v211
	v_add_u32_e32 v212, s16, v240
	v_lshl_add_u32 v212, v212, 2, 0
	v_add_u32_e32 v212, 0x11000, v212
	ds_read_b32 v212, v212
	v_add_u32_e32 v213, s16, v241
	v_lshl_add_u32 v213, v213, 2, 0
	v_add_u32_e32 v213, 0x11000, v213
	ds_read_b32 v213, v213
	v_add_u32_e32 v224, s16, v242
	v_lshl_add_u32 v224, v224, 2, 0
	v_add_u32_e32 v224, 0x11000, v224
	ds_read_b32 v224, v224
	v_add_u32_e32 v225, s16, v243
	v_lshl_add_u32 v225, v225, 2, 0
	v_add_u32_e32 v225, 0x11000, v225
	ds_read_b32 v225, v225
	v_add_u32_e32 v226, s16, v244
	v_lshl_add_u32 v226, v226, 2, 0
	v_add_u32_e32 v226, 0x11000, v226
	ds_read_b32 v226, v226
	v_add_u32_e32 v227, s16, v245
	v_lshl_add_u32 v227, v227, 2, 0
	v_add_u32_e32 v227, 0x11000, v227
	ds_read_b32 v227, v227
	s_waitcnt lgkmcnt(7)
	v_add_f32_e32 v210, v72, v210
	v_cndmask_b32_e64 v77, v77, v210, s[6:7]
	s_waitcnt lgkmcnt(6)
	v_add_f32_e32 v211, v73, v211
	v_cndmask_b32_e64 v76, v76, v211, s[22:23]
	v_mov_b32_e32 v78, 0xf149f2ca
	v_mov_b32_e32 v79, 0xf149f2ca
	s_waitcnt lgkmcnt(5)
	v_add_f32_e32 v212, v74, v212
	v_cndmask_b32_e64 v79, v79, v212, s[28:29]
	s_waitcnt lgkmcnt(4)
	v_add_f32_e32 v213, v75, v213
	v_cndmask_b32_e64 v78, v78, v213, s[30:31]
	v_pk_mul_f32 v[72:73], v[82:83], v[90:91]
	v_pk_mul_f32 v[74:75], v[80:81], v[88:89]
	v_mov_b32_e32 v80, 0xf149f2ca
	v_mov_b32_e32 v81, 0xf149f2ca
	s_waitcnt lgkmcnt(3)
	v_add_f32_e32 v224, v74, v224
	v_cndmask_b32_e64 v81, v81, v224, s[36:37]
	s_waitcnt lgkmcnt(2)
	v_add_f32_e32 v225, v75, v225
	v_cndmask_b32_e64 v80, v80, v225, s[38:39]
	v_mov_b32_e32 v82, 0xf149f2ca
	v_mov_b32_e32 v83, 0xf149f2ca
	s_waitcnt lgkmcnt(1)
	v_add_f32_e32 v226, v72, v226
	v_cndmask_b32_e64 v83, v83, v226, s[44:45]
	s_waitcnt lgkmcnt(0)
	v_add_f32_e32 v227, v73, v227
	v_cndmask_b32_e64 v82, v82, v227, s[0:1]
	v_pk_mul_f32 v[72:73], v[86:87], v[142:143]
	v_pk_mul_f32 v[74:75], v[84:85], v[140:141]
	s_addk_i32 s15, 0xe8
	v_mov_b32_e32 v84, 0xf149f2ca
	v_mov_b32_e32 v85, 0xf149f2ca
	v_add_u32_e32 v210, s15, v238
	v_lshl_add_u32 v210, v210, 2, 0
	v_add_u32_e32 v210, 0x11000, v210
	ds_read_b32 v210, v210
	v_add_u32_e32 v211, s15, v239
	v_lshl_add_u32 v211, v211, 2, 0
	v_add_u32_e32 v211, 0x11000, v211
	ds_read_b32 v211, v211
	v_add_u32_e32 v212, s15, v240
	v_lshl_add_u32 v212, v212, 2, 0
	v_add_u32_e32 v212, 0x11000, v212
	ds_read_b32 v212, v212
	v_add_u32_e32 v213, s15, v241
	v_lshl_add_u32 v213, v213, 2, 0
	v_add_u32_e32 v213, 0x11000, v213
	ds_read_b32 v213, v213
	v_add_u32_e32 v224, s15, v242
	v_lshl_add_u32 v224, v224, 2, 0
	v_add_u32_e32 v224, 0x11000, v224
	ds_read_b32 v224, v224
	v_add_u32_e32 v225, s15, v243
	v_lshl_add_u32 v225, v225, 2, 0
	v_add_u32_e32 v225, 0x11000, v225
	ds_read_b32 v225, v225
	v_add_u32_e32 v226, s15, v244
	v_lshl_add_u32 v226, v226, 2, 0
	v_add_u32_e32 v226, 0x11000, v226
	ds_read_b32 v226, v226
	v_add_u32_e32 v227, s15, v245
	v_lshl_add_u32 v227, v227, 2, 0
	v_add_u32_e32 v227, 0x11000, v227
	ds_read_b32 v227, v227
	s_waitcnt lgkmcnt(7)
	v_add_f32_e32 v210, v74, v210
	v_cndmask_b32_e64 v85, v85, v210, s[6:7]
	s_waitcnt lgkmcnt(6)
	v_add_f32_e32 v211, v75, v211
	v_cndmask_b32_e64 v84, v84, v211, s[22:23]
	v_mov_b32_e32 v74, 0xf149f2ca
	v_mov_b32_e32 v75, 0xf149f2ca
	s_waitcnt lgkmcnt(5)
	v_add_f32_e32 v212, v72, v212
	v_cndmask_b32_e64 v75, v75, v212, s[28:29]
	s_waitcnt lgkmcnt(4)
	v_add_f32_e32 v213, v73, v213
	v_cndmask_b32_e64 v74, v74, v213, s[30:31]
	v_pk_mul_f32 v[66:67], v[70:71], v[66:67]
	v_pk_mul_f32 v[64:65], v[68:69], v[64:65]
	v_mov_b32_e32 v68, 0xf149f2ca
	v_mov_b32_e32 v69, 0xf149f2ca
	s_waitcnt lgkmcnt(3)
	v_add_f32_e32 v224, v64, v224
	v_cndmask_b32_e64 v69, v69, v224, s[36:37]
	s_waitcnt lgkmcnt(2)
	v_add_f32_e32 v225, v65, v225
	v_cndmask_b32_e64 v68, v68, v225, s[38:39]
	v_mov_b32_e32 v64, 0xf149f2ca
	v_mov_b32_e32 v65, 0xf149f2ca
	s_waitcnt lgkmcnt(1)
	v_add_f32_e32 v226, v66, v226
	v_cndmask_b32_e64 v65, v65, v226, s[44:45]
	s_waitcnt lgkmcnt(0)
	v_add_f32_e32 v227, v67, v227
	v_cndmask_b32_e64 v64, v64, v227, s[0:1]
	s_branch .Lna2_184
